# all remaining LDS pointer-table fetches read with ds_read_b64 instead of flat loads (same waits plus lgkmcnt); final RMSNorm double-buffered
# speedup vs baseline: 1.0015x; 1.0015x over previous
; __device__ __forceinline__ const void* ldp(int i) {
;     const unsigned long long v = *(const volatile unsigned long long*)(g_smem + PTR_OFF + 8 * i);
;     const unsigned lo = __builtin_amdgcn_readfirstlane((unsigned)v), hi = __builtin_amdgcn_readfirstlane((unsigned)(v >> 32));
;     return (const void*)(const __attribute__((address_space(1))) void*)(((unsigned long long)hi << 32) | lo);
; }
; __global__ void __launch_bounds__(512, 2) fwd_megakernel(Params p) {
;     ...
;     __syncthreads();
;     bf16_t* wt = (bf16_t*)(((unsigned char*)ldp(38)) + OFF_WT); bf16_t* xn = (bf16_t*)(((unsigned char*)ldp(38)) + OFF_XN); float* h = ((float*)ldp(37));
;     float* part = (float*)(((unsigned char*)ldp(38)) + OFF_PART);
;     unsigned char* RA = ((unsigned char*)ldp(38)) + OFF_A; unsigned char* RB = ((unsigned char*)ldp(38)) + OFF_B;
.LBB0_3:
	s_or_b64 exec, exec, s[20:21]
	s_mov_b64 s[40:41], src_shared_base
	s_add_i32 s40, 0, 0x23f30
	s_cmp_lg_u32 s40, -1
	s_cselect_b32 s4, s40, 0
	s_cselect_b32 s5, s41, 0
	v_mov_b64_e32 v[12:13], s[4:5]
	s_waitcnt lgkmcnt(0)
	s_barrier
	ds_read_b64 v[2:3], v12
	s_waitcnt vmcnt(0) lgkmcnt(0)
	ds_read_b64 v[4:5], v12
	s_waitcnt vmcnt(0) lgkmcnt(0)
	v_mov_b32_e32 v1, 0x80
	v_mov_b32_e32 v185, 0
	v_mov_b32_e32 v235, 0x358637bd
	v_mov_b32_e32 v236, 0x260
	v_mov_b32_e32 v237, 0x3c088889
	v_mov_b32_e32 v140, 0x41b17218
	v_mov_b32_e32 v141, 0xc00
	v_mov_b32_e32 v242, 0x7f800000
	v_mov_b32_e32 v186, 0x3f317218
	v_mov_b32_e32 v188, 0x46814157
	v_mov_b32_e32 v189, 0x3c62f49b
	v_mov_b32_e32 v190, 0x7030ad4a
	v_mov_b32_e32 v191, 0xbce952c7
	v_mov_b32_e32 v192, 0xe733b81f
	v_mov_b32_e32 v193, 0x3d6ae7f3
	v_mov_b32_e32 v194, 0x13a86d09
	v_mov_b32_e32 v195, 0xbde61246
	v_mov_b32_e32 v196, 0x67f544e4
	v_mov_b32_e32 v197, 0x3e5ae645
	v_mov_b32_e32 v198, 0xa556c734
	v_mov_b32_e32 v199, 0xbec71de3
	v_mov_b32_e32 v200, 0x1a01a01a
	v_mov_b32_e32 v201, 0x3f2a01a0
	v_mov_b32_e32 v202, 0x11111111
	v_mov_b32_e32 v203, 0xbf811111
	v_mov_b32_e32 v204, 0x55555555
	v_mov_b32_e32 v205, 0x3fc55555
	s_movk_i32 s67, 0x1800
	s_movk_i32 s78, 0x1000
	s_movk_i32 s79, 0x3000
	s_movk_i32 s92, 0x60
	s_mov_b32 s71, 0x3fb8aa3b
	s_movk_i32 s93, 0x2400
	s_movk_i32 s89, 0xc00
	s_mov_b32 s70, 0x7f800000
	s_movk_i32 s85, 0x2000
	s_mov_b32 s84, 0x14c1e000
	s_mov_b32 s38, 0x18c1e000
	s_movk_i32 s94, 0x7000
	s_mov_b32 s95, 0xc4ffe000
	s_mov_b32 s96, 0xc2ce8ed0
	s_mov_b32 s97, 0x42b17218
	s_movk_i32 s33, 0x2c00
	s_movk_i32 s88, 0x7fff
	s_movk_i32 s54, 0x1600
	s_mov_b64 s[90:91], 0
	s_mov_b32 s26, 0x3d4ccccd
	s_mov_b64 s[68:69], 0x400
	s_mov_b64 s[74:75], 0x80
	s_waitcnt lgkmcnt(0)
	v_readfirstlane_b32 s76, v2
	v_readfirstlane_b32 s4, v4
	v_readfirstlane_b32 s3, v5
	s_add_u32 s4, s4, 0x3c00000
	s_addc_u32 s5, s3, 0
	s_add_i32 s3, 0, 0x23f28
	v_writelane_b32 v254, s4, 2
	s_cmp_lg_u32 s3, -1
	s_cselect_b32 s3, s3, 0
	v_writelane_b32 v254, s5, 3
	s_cselect_b32 s4, s41, 0
	v_mov_b32_e32 v14, s3
	v_mov_b32_e32 v15, s4
	ds_read_b64 v[4:5], v14
	s_waitcnt vmcnt(0) lgkmcnt(0)
	ds_read_b64 v[6:7], v12
	s_waitcnt vmcnt(0) lgkmcnt(0)
	ds_read_b64 v[8:9], v12
	s_waitcnt vmcnt(0) lgkmcnt(0)
	ds_read_b64 v[10:11], v12
	s_waitcnt vmcnt(0) lgkmcnt(0)
	v_readfirstlane_b32 s66, v3
	s_mul_hi_i32 s3, s2, 0x2aaaaaab
	v_lshrrev_b32_e32 v12, 20, v0
	v_lshrrev_b32_e32 v0, 10, v0
	v_or_b32_e32 v0, v0, v12
	v_and_or_b32 v0, v0, s55, v234
	v_mbcnt_lo_u32_b32 v13, -1, 0
	v_mbcnt_hi_u32_b32 v243, -1, v13
	s_waitcnt lgkmcnt(0)
	v_readfirstlane_b32 s15, v5
	v_readfirstlane_b32 s5, v6
	v_readfirstlane_b32 s4, v7
	s_add_u32 s10, s5, 0x22d00000
	v_readfirstlane_b32 s7, v8
	s_addc_u32 s11, s4, 0
	v_readfirstlane_b32 s6, v9
	v_writelane_b32 v254, s10, 4
	s_add_u32 s4, s7, 0x7c00000
	s_addc_u32 s5, s6, 0
	v_writelane_b32 v254, s11, 5
	v_readfirstlane_b32 s9, v10
	v_writelane_b32 v254, s4, 6
	v_readfirstlane_b32 s8, v11
	v_readfirstlane_b32 s14, v4
	v_writelane_b32 v254, s5, 7
	s_add_u32 s4, s9, 0x12c00000
	s_addc_u32 s5, s8, 0
	v_writelane_b32 v254, s4, 8
	s_nop 1
	v_writelane_b32 v254, s5, 9
	s_add_u32 s4, s7, 0x13c00000
	s_addc_u32 s5, s6, 0
	v_writelane_b32 v254, s4, 10
	s_nop 1
	v_writelane_b32 v254, s5, 11
	s_add_u32 s4, s76, 0x2780000
	s_addc_u32 s5, s66, 0
	v_writelane_b32 v254, s4, 12
	s_nop 1
	v_writelane_b32 v254, s5, 13
	s_add_u32 s4, s76, 0x2480000
	s_addc_u32 s5, s66, 0
	v_writelane_b32 v254, s4, 14
	s_nop 1
	v_writelane_b32 v254, s5, 15
	s_add_u32 s4, s76, 0x1e80000
	s_addc_u32 s5, s66, 0
	v_writelane_b32 v254, s4, 16
	s_nop 1
	v_writelane_b32 v254, s5, 17
	s_lshl_b32 s4, s2, 9
	s_add_u32 s0, s0, 0x138
	v_writelane_b32 v254, s4, 18
	s_addc_u32 s1, s1, 0
	v_writelane_b32 v254, s0, 19
	s_cmpk_lt_i32 s2, 0x1800
	s_nop 0
	v_writelane_b32 v254, s1, 20
	s_cselect_b64 s[0:1], -1, 0
	v_writelane_b32 v254, s0, 21
	s_nop 1
	v_writelane_b32 v254, s1, 22
	s_lshr_b32 s0, s3, 31
	s_lshr_b32 s1, s3, 10
	s_add_i32 s0, s1, s0
	s_mulk_i32 s0, 0x1800
	s_sub_i32 s0, s2, s0
	s_bfe_i32 s4, s0, 0x100004
	s_lshl_b32 s1, s0, 1
	s_lshr_b32 s3, s0, 4
	s_mulk_i32 s0, 0x2aab
	s_mulk_i32 s4, 0x2aab
	s_and_b32 s5, s1, 30
	s_lshr_b32 s1, s0, 31
	s_ashr_i32 s0, s0, 22
	s_lshr_b32 s10, s4, 31
	s_lshr_b32 s4, s4, 18
	s_add_i32 s0, s0, s1
	s_add_i32 s4, s4, s10
	s_ashr_i32 s1, s0, 31
	s_mul_i32 s4, s4, 24
	s_lshl_b64 s[10:11], s[0:1], 11
	s_sub_i32 s0, s3, s4
	s_sext_i32_i16 s0, s0
	s_ashr_i32 s1, s0, 2
	s_lshl_b32 s12, s0, 6
	s_mulk_i32 s0, 0x81
	v_writelane_b32 v254, s0, 23
	s_ashr_i32 s13, s12, 31
	s_and_b32 s1, s1, -2
	v_writelane_b32 v254, s12, 24
	s_lshr_b32 s3, 0x800, s1
	s_lshr_b32 s0, 32, s1
	v_writelane_b32 v254, s13, 25
	v_writelane_b32 v254, s3, 26
	v_writelane_b32 v254, s1, 27
	s_sub_i32 s1, 5, s1
	s_lshr_b32 s1, s5, s1
	s_or_b32 s10, s10, s1
	s_add_i32 s0, s0, -1
	v_writelane_b32 v254, s10, 28
;     ...
;     const int first = ((int)blockIdx.x + rot) % (int)gridDim.x;
; __device__ void convert_phase(unsigned char* smem, const Params& p, int l) {
;     ...
;       conv_tiles(tile, wt + W_UP1, 5632, 1024, 0, [=](int k, int r) { const int col = (r >> 5) * 16 + (r & 15); return gn[k] * (((r >> 4) & 1) ? wu[(size_t)k * DFF + col] : wg[(size_t)k * DFF + col]); }); }
;     { const float* wd = ((const float*)ldp(4)) + uo; conv_tiles(tile, wt + W_DN1, 1024, 2816, 37, [=](int k, int r) { return wd[(size_t)k * DM + r]; }); }
;     { const float* wi = ((const float*)ldp(6)) + (size_t)l * DM * INC; const float* gn = ((const float*)ldp(5)) + l * DM;
;       conv_tiles(tile, wt + W_HYRG, 2560, 1024, 71, [=](int k, int r) { const int col = r < HYC ? r : r + QKVC; return gn[k] * wi[(size_t)k * INC + col]; });
;       conv_tiles(tile, wt + W_QKV, 4608, 1024, 113, [=](int k, int r) { return gn[k] * wi[(size_t)k * INC + HYC + r]; }); }
;     { const float* wgt = ((const float*)ldp(26)) + (size_t)l * DM * 3072; const float* gn = ((const float*)ldp(5)) + l * DM; conv_tiles(tile, wt + W_GATE, 3072, 1024, 151, [=](int k, int r) { return gn[k] * wgt[(size_t)k * 3072 + r]; }); }
;     { const float* a = ((const float*)ldp(28)) + (size_t)l * 512 * DM; conv_tiles(tile, wt + W_PCAT + 0, 1024, 512, 193, [=](int k, int r) { return a[(size_t)k * DM + r]; }, 1536); }
;     { const float* a = ((const float*)ldp(29)) + (size_t)l * 512 * DM; conv_tiles(tile, wt + W_PCAT + 512, 1024, 512, 211, [=](int k, int r) { return a[(size_t)k * DM + r]; }, 1536); }
;     { const float* a = ((const float*)ldp(30)) + (size_t)l * 512 * DM; conv_tiles(tile, wt + W_PCAT + 1024, 1024, 512, 229, [=](int k, int r) { return a[(size_t)k * DM + r]; }, 1536); }
;     { const float* a = ((const float*)ldp(31)) + (size_t)l * DM * DM; conv_tiles(tile, wt + W_OUT, 1024, 1024, 17, [=](int k, int r) { return a[(size_t)k * DM + r]; }); }
;     { const float* wg = ((const float*)ldp(33)) + uo; const float* wu = ((const float*)ldp(34)) + uo; const float* gn = ((const float*)ldp(32)) + l * DM;
;       conv_tiles(tile, wt + W_UP2, 5632, 1024, 53, [=](int k, int r) { const int col = (r >> 5) * 16 + (r & 15); return gn[k] * (((r >> 4) & 1) ? wu[(size_t)k * DFF + col] : wg[(size_t)k * DFF + col]); }); }
	s_and_b32 s0, s0, s5
	s_nop 0
	v_writelane_b32 v254, s11, 29
	v_writelane_b32 v254, s0, 30
	s_lshl_b32 s0, s0, 6
	v_writelane_b32 v254, s0, 31
	s_add_u32 s0, s76, 0x1580000
	s_addc_u32 s1, s66, 0
	v_writelane_b32 v254, s0, 32
	s_cmpk_lt_i32 s2, 0x1000
	s_nop 0
	v_writelane_b32 v254, s1, 33
	s_cselect_b64 s[0:1], -1, 0
	v_writelane_b32 v254, s0, 34
	s_cmpk_lt_i32 s2, 0x80
	s_nop 0
	v_writelane_b32 v254, s1, 35
	s_cselect_b64 s[0:1], -1, 0
	v_writelane_b32 v254, s0, 36
	s_cmpk_lt_i32 s2, 0x1080
	s_nop 0
	v_writelane_b32 v254, s1, 37
	s_cselect_b64 s[0:1], -1, 0
	v_writelane_b32 v254, s0, 38
	s_nop 1
	v_writelane_b32 v254, s1, 39
	s_add_u32 s0, s76, 0x3a00000
	s_addc_u32 s1, s66, 0
	v_writelane_b32 v254, s0, 40
	s_nop 1
	v_writelane_b32 v254, s1, 41
	s_add_u32 s0, s9, 0x16c00000
	s_addc_u32 s1, s8, 0
	v_writelane_b32 v254, s0, 42
	s_cmpk_lt_i32 s2, 0x200
	s_nop 0
	v_writelane_b32 v254, s1, 43
	s_cselect_b64 s[0:1], -1, 0
	s_lshl_b32 s77, s2, 3
	v_writelane_b32 v254, s0, 44
	s_cmpk_lt_i32 s2, 0x3000
	s_nop 0
	v_writelane_b32 v254, s1, 45
	s_cselect_b64 s[0:1], -1, 0
	v_writelane_b32 v254, s0, 46
	s_cmpk_lt_i32 s2, 0x100
	s_nop 0
	v_writelane_b32 v254, s1, 47
	s_cselect_b64 s[0:1], -1, 0
	v_writelane_b32 v254, s0, 48
	s_nop 1
	v_writelane_b32 v254, s1, 49
	s_add_u32 s0, s76, 0x1080000
	s_addc_u32 s1, s66, 0
	v_writelane_b32 v254, s0, 50
	s_nop 1
	v_writelane_b32 v254, s1, 51
	s_add_u32 s0, s7, 0xdc00000
	s_addc_u32 s1, s6, 0
	v_writelane_b32 v254, s0, 52
	s_add_i32 s4, s2, 0x71
	s_add_i32 s5, s2, 0x97
	v_writelane_b32 v254, s1, 53
	s_add_i32 s0, s2, 37
	s_add_i32 s1, s2, 0x47
	s_add_i32 s6, s2, 0xc1
	s_add_i32 s7, s2, 0xd3
	s_add_i32 s8, s2, 0xe5
	s_add_i32 s9, s2, 17
	s_add_i32 s10, s2, 53
	s_add_i32 s11, s2, 0x61
	s_add_i32 s12, s2, 0x83
	s_cmp_eq_u32 s2, 0
	s_cselect_b64 s[16:17], -1, 0
	s_ashr_i32 s3, s2, 31
	s_lshr_b32 s13, s3, 29
	v_writelane_b32 v254, s16, 54
	s_add_i32 s13, s2, s13
	s_nop 0
	v_writelane_b32 v254, s17, 55
	s_ashr_i32 s16, s13, 3
	s_and_b32 s13, s13, -8
	s_sub_i32 s13, s2, s13
	s_cmp_lg_u64 s[14:15], 0
	v_writelane_b32 v254, s16, 56
	s_cselect_b64 s[86:87], -1, 0
	s_ashr_i32 s16, s0, 31
	v_writelane_b32 v254, s16, 57
	s_abs_i32 s0, s0
	v_writelane_b32 v254, s0, 58
	s_ashr_i32 s0, s1, 31
	v_writelane_b32 v254, s0, 59
	s_abs_i32 s0, s1
	v_writelane_b32 v254, s0, 60
	s_ashr_i32 s0, s4, 31
	v_writelane_b32 v254, s0, 61
	s_abs_i32 s0, s4
	v_writelane_b32 v254, s0, 62
	s_ashr_i32 s0, s5, 31
	v_writelane_b32 v254, s0, 63
	s_abs_i32 s0, s5
	v_writelane_b32 v255, s0, 0
	s_ashr_i32 s0, s6, 31
	v_writelane_b32 v255, s0, 1
	s_abs_i32 s0, s6
	v_writelane_b32 v255, s0, 2
	s_ashr_i32 s0, s7, 31
	v_writelane_b32 v255, s0, 3
	s_abs_i32 s0, s7
	v_writelane_b32 v255, s0, 4
	s_ashr_i32 s0, s8, 31
	v_writelane_b32 v255, s0, 5
	s_abs_i32 s0, s8
	v_writelane_b32 v255, s0, 6
	s_ashr_i32 s0, s9, 31
	v_writelane_b32 v255, s0, 7
	s_abs_i32 s0, s9
	v_writelane_b32 v255, s0, 8
	s_ashr_i32 s0, s10, 31
	v_writelane_b32 v255, s0, 9
	s_abs_i32 s0, s10
	v_writelane_b32 v255, s0, 10
	s_ashr_i32 s0, s11, 31
	v_writelane_b32 v255, s0, 11
	s_abs_i32 s0, s11
	v_writelane_b32 v255, s0, 12
	s_ashr_i32 s0, s12, 31
	v_writelane_b32 v255, s0, 13
	s_abs_i32 s0, s12
	v_writelane_b32 v255, s0, 14
	v_writelane_b32 v255, s13, 15
	s_lshr_b32 s0, s13, 31
	v_writelane_b32 v255, s0, 16
	s_abs_i32 s0, s2
	v_writelane_b32 v255, s0, 17
	s_lshl_b32 s0, s2, 12
	v_writelane_b32 v255, s0, 18
	s_lshl_b32 s0, s2, 6
	v_writelane_b32 v255, s0, 19
	s_add_u32 s0, s14, 0xc00
	v_writelane_b32 v255, s14, 20
	s_addc_u32 s1, s15, 0
	s_mov_b32 s4, 0xbe800000
	v_writelane_b32 v255, s15, 21
	v_writelane_b32 v255, s0, 22
	s_nop 1
	v_writelane_b32 v255, s1, 23
	v_sub_co_u32_e64 v1, s[0:1], s2, v1
	s_nop 1
	v_writelane_b32 v255, s0, 24
	s_nop 1
	v_writelane_b32 v255, s1, 25
	v_readfirstlane_b32 s0, v1
	s_nop 1
	v_writelane_b32 v255, s0, 26
	s_add_i32 s0, 0, 0x13200
	v_writelane_b32 v255, s0, 27
	s_add_i32 s0, 0, 0x3e00
	v_writelane_b32 v255, s0, 28
	s_add_i32 s0, 0, 0x10100
	v_writelane_b32 v255, s0, 29
	s_add_i32 s0, 0, 0x12110
	v_writelane_b32 v255, s0, 30
	s_add_i32 s0, 0, 0x14120
	v_writelane_b32 v255, s0, 31
	s_add_i32 s0, 0, 0x16130
	v_writelane_b32 v255, s0, 32
	s_add_i32 s0, 0, 0x18140
	v_writelane_b32 v255, s0, 33
	s_add_i32 s0, 0, 0x1a150
	v_writelane_b32 v255, s0, 34
	s_add_i32 s0, 0, 0x1c160
	v_writelane_b32 v255, s0, 35
	s_add_i32 s0, 0, 0x1e170
	v_writelane_b32 v255, s0, 36
	s_add_i32 s0, 0, 0xc80
	v_writelane_b32 v255, s0, 37
	v_cmp_eq_u32_e64 s[0:1], 0, v0
	s_nop 1
	v_writelane_b32 v255, s0, 38
	s_nop 1
	v_writelane_b32 v255, s1, 39
	s_mov_b32 s1, 0x3ff921fb
	v_writelane_b32 v255, s0, 40
	s_nop 1
	v_writelane_b32 v255, s1, 41
	v_writelane_b32 v255, s40, 42
	s_nop 1
	v_writelane_b32 v255, s41, 43
	v_writelane_b32 v255, s40, 44
	v_writelane_b32 v255, s66, 45
	v_writelane_b32 v255, s76, 46
	v_writelane_b32 v255, s77, 47
	s_branch .LBB0_6

; __global__ void __launch_bounds__(512, 2) fwd_megakernel(Params p) {
;     ...
;         case 15: d.kind = 4; d.A = (const bf16_t*)(((unsigned char*)ldp(38)) + OFF_YA); d.Bt = wt + W_PCAT; d.N = 1024; d.K = 1536; d.q0 = RA; d.p1 = RA + 192 * MiB; break;
.LBB0_16:
	s_andn2_b64 vcc, exec, s[0:1]
	s_mov_b32 s5, 1
	s_cbranch_vccnz .LBB0_19
	s_cmp_lg_u32 s40, -1
	s_cselect_b32 s0, s40, 0
	s_cselect_b32 s1, s41, 0
	s_waitcnt vmcnt(3)
	v_mov_b32_e32 v0, s0
	v_mov_b32_e32 v1, s1
	ds_read_b64 v[0:1], v0
	s_waitcnt vmcnt(0) lgkmcnt(0)
	v_readlane_b32 s42, v254, 6
	v_readlane_b32 s52, v254, 10
	v_readlane_b32 s48, v254, 14
	s_movk_i32 s24, 0x600
	s_mov_b64 s[18:19], -1
	s_mov_b32 s5, 4
	s_mov_b32 s58, 0
	v_readlane_b32 s43, v254, 7
	v_readlane_b32 s53, v254, 11
	s_mov_b64 s[44:45], 0
	v_readlane_b32 s49, v254, 15
	s_waitcnt lgkmcnt(0)
	v_readfirstlane_b32 s1, v0
	v_readfirstlane_b32 s0, v1
	s_add_u32 s28, s1, 0x1cc00000
	s_addc_u32 s29, s0, 0
	s_branch .LBB0_20

; #define TIDX tid_opaque()
; __device__ void attn_merge_phase(const Params& p, int chunk) {
;     const bf16_t* og = (const bf16_t*)(((unsigned char*)ldp(38)) + OFF_A); const float* lse = (const float*)(((unsigned char*)ldp(38)) + OFF_XC); bf16_t* yb = (bf16_t*)(((unsigned char*)ldp(38)) + OFF_YA) + 512;
;     const int total = MT * 64;
;     for (int idx = blockIdx.x * 512 + TIDX; idx < total; idx += gridDim.x * 512) {
;         const int e8 = idx & 7, j = (idx >> 3) & 7; const size_t tok = (size_t)(idx >> 6);
; __global__ void __launch_bounds__(512, 2) fwd_megakernel(Params p) {
;     ...
;         case 14: d.kind = 3; d.A = xn; d.Bt = wt + W_GATE; d.N = 3072; d.K = 1024; d.p0 = RA; d.q0 = ((const float*)ldp(27)) + l * 3072; d.q3 = part; break;
.LBB0_22:
	s_mov_b32 s8, 0
	v_writelane_b32 v255, s8, 58
	s_and_b64 vcc, exec, s[0:1]
	s_cbranch_vccz .LBB0_187
	s_cmp_lt_i32 s27, 12
	s_mov_b64 s[0:1], -1
	s_cbranch_scc1 .LBB0_152
	s_cmp_lt_i32 s27, 13
	s_cbranch_scc1 .LBB0_32
	s_mov_b64 s[6:7], -1
	s_cmp_gt_i32 s27, 13
	s_cbranch_scc0 .LBB0_27
	s_add_i32 s0, 0, 0x23ed8
	s_cmp_lg_u32 s0, -1
	s_cselect_b32 s0, s0, 0
	s_cselect_b32 s1, s41, 0
	s_waitcnt vmcnt(3)
	v_mov_b32_e32 v0, s0
	v_mov_b32_e32 v1, s1
	ds_read_b64 v[0:1], v0
	s_waitcnt vmcnt(0) lgkmcnt(0)
	s_mul_i32 s0, s30, 0x3000
	s_waitcnt lgkmcnt(0)
	v_readfirstlane_b32 s5, v0
	v_readfirstlane_b32 s1, v1
	s_add_u32 s42, s5, s0
	s_addc_u32 s43, s1, 0
	s_mov_b64 s[0:1], 0
.LBB0_27:
	s_andn2_b64 vcc, exec, s[0:1]
	s_cbranch_vccnz .LBB0_240
	s_cmp_lg_u32 s40, -1
	s_cselect_b32 s0, s40, 0
	s_cselect_b32 s1, s41, 0
	s_waitcnt vmcnt(3)
	v_mov_b64_e32 v[0:1], s[0:1]
	ds_read_b64 v[2:3], v0
	s_waitcnt vmcnt(0) lgkmcnt(0)
	ds_read_b64 v[4:5], v0
	s_waitcnt vmcnt(0) lgkmcnt(0)
	ds_read_b64 v[8:9], v0
	s_waitcnt vmcnt(0) lgkmcnt(0)
	v_mov_b32_e32 v0, v234
	v_readlane_b32 s1, v254, 18
	s_mov_b32 s0, 0x200000
	s_waitcnt lgkmcnt(0)
	v_readfirstlane_b32 s9, v3
	v_add_u32_e32 v6, s1, v0
	v_readfirstlane_b32 s10, v2
	v_readfirstlane_b32 s5, v5
	v_readfirstlane_b32 s7, v4
	v_readfirstlane_b32 s6, v9
	v_readfirstlane_b32 s8, v8
	v_cmp_gt_i32_e32 vcc, s0, v6
	s_and_saveexec_b64 s[0:1], vcc
	s_cbranch_execz .LBB0_31
	v_readlane_b32 s12, v254, 19
	s_add_u32 s10, s10, 0x7c00000
	v_readlane_b32 s13, v254, 20
	s_addc_u32 s11, s9, 0
	s_load_dword s9, s[12:13], 0x0
	s_add_u32 s12, s7, 0x1ac00000
	s_addc_u32 s13, s5, 0
	s_add_u32 s14, s8, 0x1cc00400
	s_addc_u32 s15, s6, 0
	v_readlane_b32 s6, v255, 18
	s_waitcnt lgkmcnt(0)
	s_lshl_b32 s5, s9, 9
	s_lshl_b32 s8, s9, 12
	v_lshl_add_u32 v7, v0, 3, s6
	s_mov_b64 s[6:7], 0
	v_mov_b64_e32 v[0:1], s[12:13]
	v_mov_b64_e32 v[2:3], s[10:11]
	v_mov_b64_e32 v[4:5], s[14:15]

; #define TIDX tid_opaque()
; __device__ void attn_phase(unsigned char* smem, const Params& p, int chunk) {
;     bf16_t* qkv = (bf16_t*)(((unsigned char*)ldp(38)) + OFF_A); float* lse = (float*)(((unsigned char*)ldp(38)) + OFF_XC);
;     const float* biastab = (const float*)(((unsigned char*)ldp(38)) + OFF_SM) + 1024;
;     const int tid = TIDX, lane = tid & 63, w = tid >> 6, half = w >> 2, qs = w & 3, r16 = lane & 15, g4 = lane >> 4;
;     bf16_t* Ks = (bf16_t*)smem; bf16_t* Vs = (bf16_t*)(smem + AKR * KST * 2); float* bs = (float*)(smem + AKR * KST * 2 + AKR * VSR * 2);
;     const int npair = NB * 24 * 32 / 2;
;     u32x4 kreg[5], vreg[5]; bf16x8 qn[2]; float bn = 0.f;
;     ...
;     const int nrep = ((REP >> 5) & 1) + 1;
;     int pair_ = blockIdx.x;
;     if (pair_ < npair * nrep) ATT_PREFETCH(pair_ % npair);
.LBB0_33:
	s_cmp_lg_u32 s40, -1
	s_cselect_b32 s0, s40, 0
	s_cselect_b32 s1, s41, 0
	s_waitcnt vmcnt(3)
	v_mov_b64_e32 v[0:1], s[0:1]
	ds_read_b64 v[2:3], v0
	s_waitcnt vmcnt(0) lgkmcnt(0)
	ds_read_b64 v[4:5], v0
	s_waitcnt vmcnt(0) lgkmcnt(0)
	ds_read_b64 v[0:1], v0
	s_waitcnt vmcnt(0) lgkmcnt(0)
	v_readlane_b32 s14, v254, 21
	v_readlane_b32 s15, v254, 22
	v_mov_b32_e32 v102, v234
	s_movk_i32 s5, 0x880
	v_cndmask_b32_e64 v6, 0, 1, s[14:15]
	v_cmp_ne_u32_e64 s[0:1], 1, v6
	v_lshlrev_b32_e32 v6, 4, v102
	v_ashrrev_i32_e32 v104, 3, v102
	v_mov_b32_e32 v112, 0
	v_ashrrev_i32_e32 v103, 8, v102
	v_bfe_u32 v46, v102, 6, 2
	v_and_b32_e32 v45, 15, v102
	v_bfe_u32 v44, v102, 4, 2
	v_cmp_gt_i32_e64 s[8:9], s5, v102
	v_and_b32_e32 v40, 0x70, v6
	s_waitcnt lgkmcnt(0)
	v_readfirstlane_b32 s6, v2
	v_readfirstlane_b32 s7, v3
	s_add_u32 s6, s6, 0x7c00000
	v_readfirstlane_b32 s11, v0
	s_addc_u32 s7, s7, 0
	v_readfirstlane_b32 s10, v1
	s_add_u32 s28, s11, 0x22c01000
	s_addc_u32 s29, s10, 0
	s_movk_i32 s10, 0x100
	v_readfirstlane_b32 s5, v5
	v_readfirstlane_b32 s12, v4
	s_andn2_b64 vcc, exec, s[14:15]
	v_cmp_gt_i32_e64 s[10:11], s10, v104
	s_cbranch_vccnz .LBB0_47
	v_readlane_b32 s14, v254, 24
	v_readlane_b32 s15, v254, 25
	s_lshl_b64 s[14:15], s[14:15], 1
	v_readlane_b32 s13, v254, 31
	s_add_u32 s14, s6, s14
	v_mov_b32_e32 v0, v185
	v_add_u32_e32 v4, s13, v104
	s_addc_u32 s15, s7, s15
	v_subrev_u32_e32 v184, 64, v4
	s_and_b64 s[8:9], s[8:9], s[10:11]
	v_mov_b32_e32 v2, v0
	v_mov_b32_e32 v3, v0
	v_cmp_lt_i32_e32 vcc, 63, v4
	v_readlane_b32 s10, v254, 26
	v_mov_b32_e32 v41, v185
	v_mov_b32_e32 v1, v0
	s_and_b64 s[8:9], s[8:9], vcc
	v_cmp_gt_i32_e32 vcc, s10, v184
	v_mov_b64_e32 v[6:7], v[2:3]
	v_lshl_add_u64 v[42:43], s[14:15], 0, v[40:41]
	s_and_b64 s[10:11], s[8:9], vcc
	v_mov_b64_e32 v[4:5], v[0:1]
	s_and_saveexec_b64 s[8:9], s[10:11]
	v_readlane_b32 s14, v254, 28
	v_readlane_b32 s15, v254, 29
	s_cbranch_execz .LBB0_36
	v_readlane_b32 s10, v254, 27
	s_nop 1
	v_lshlrev_b64 v[0:1], s10, v[184:185]
	v_lshl_add_u64 v[0:1], v[0:1], 0, s[14:15]
	v_mad_u64_u32 v[2:3], s[10:11], v0, s93, v[42:43]
	v_mov_b32_e32 v0, v3
	v_mad_u64_u32 v[0:1], s[10:11], v1, s93, v[0:1]
	v_add_co_u32_e32 v4, vcc, 0x1000, v2
	v_mov_b32_e32 v3, v0
	s_nop 0
	v_addc_co_u32_e32 v5, vcc, 0, v0, vcc
	global_load_dwordx4 v[0:3], v[2:3], off offset:3072
	s_nop 0
	global_load_dwordx4 v[4:7], v[4:5], off offset:2048

; #define RP(bit) for (int rp_ = 0; rp_ < (((REP >> (bit)) & 1) ? 2 : 1); ++rp_)
; #define TIDX tid_opaque()
; __device__ void ya_transpose_phase(unsigned char* smem, int first_wg, int n_wg) {
;     bf16_t* tile = (bf16_t*)smem;
;     const bf16_t* yaT = (const bf16_t*)(((unsigned char*)ldp(38)) + OFF_A); bf16_t* ya = (bf16_t*)(((unsigned char*)ldp(38)) + OFF_YA);
;     const int tid = TIDX;
;     const int ntile = (MT / 64) * (HYW / 64);
;     for (int t = (int)blockIdx.x - first_wg; t < ntile; t += n_wg) {
;         const int cblk = t % (HYW / 64), rblk = t / (HYW / 64); const int b = rblk >> 5, t0 = (rblk & 31) * 64, c0 = cblk * 64;
;         __syncthreads();
;         { const int cc = tid >> 3, t8 = tid & 7; *(u32x4*)(tile + cc * 72 + t8 * 8) = *(const u32x4*)(yaT + ((size_t)(c0 + cc) * NB + b) * SEQ + t0 + t8 * 8); }
;         __syncthreads();
;         { const int tt = tid >> 3, c8 = tid & 7; unsigned short v[8];
; #pragma unroll
;           for (int i = 0; i < 8; ++i) v[i] = tile[(c8 * 8 + i) * 72 + tt];
;           u32x4 w; w.x = (unsigned)v[0] | ((unsigned)v[1] << 16); w.y = (unsigned)v[2] | ((unsigned)v[3] << 16); w.z = (unsigned)v[4] | ((unsigned)v[5] << 16); w.w = (unsigned)v[6] | ((unsigned)v[7] << 16);
;           *(u32x4*)(ya + ((size_t)b * SEQ + t0 + tt) * 1536 + c0 + c8 * 8) = w; }
; __global__ void __launch_bounds__(512, 2) fwd_megakernel(Params p) {
;     ...
;         case 10: if (gridDim.x >= 256 && blockIdx.x >= 128) ya_transpose_phase(smem, 128, (int)gridDim.x - 128); else { if (gridDim.x < 256) ya_transpose_phase(smem, 0, (int)gridDim.x); RP(13) rg_scan_phase(smem, p); } break;
.LBB0_155:
	s_andn2_b64 vcc, exec, s[0:1]
	s_mov_b32 s23, 0x5040100
	s_mov_b32 s31, 0x12c01000
	s_mov_b32 s34, 0x16c01000
	s_cbranch_vccnz .LBB0_184
	v_readlane_b32 s0, v254, 19
	v_readlane_b32 s1, v254, 20
	s_load_dword s5, s[0:1], 0x0
	v_readlane_b32 s6, v255, 24
	v_readlane_b32 s7, v255, 25
	s_waitcnt lgkmcnt(0)
	s_cmpk_lt_u32 s5, 0x100
	s_cselect_b64 s[0:1], -1, 0
	s_or_b64 s[8:9], s[0:1], s[6:7]
	s_mov_b64 s[6:7], -1
	s_and_b64 vcc, exec, s[8:9]
	s_cbranch_vccnz .LBB0_161
	s_cmp_lg_u32 s40, -1
	s_cselect_b32 s6, s40, 0
	s_cselect_b32 s7, s41, 0
	s_waitcnt vmcnt(3)
	v_mov_b64_e32 v[0:1], s[6:7]
	ds_read_b64 v[2:3], v0
	s_waitcnt vmcnt(0) lgkmcnt(0)
	ds_read_b64 v[4:5], v0
	s_waitcnt vmcnt(0) lgkmcnt(0)
	v_readlane_b32 s6, v254, 38
	v_readlane_b32 s7, v254, 39
	v_mov_b32_e32 v1, v234
	s_andn2_b64 vcc, exec, s[6:7]
	s_waitcnt lgkmcnt(0)
	v_readfirstlane_b32 s7, v3
	v_readfirstlane_b32 s6, v2
	v_readfirstlane_b32 s9, v5
	v_readfirstlane_b32 s8, v4
	s_cbranch_vccnz .LBB0_160
	v_ashrrev_i32_e32 v0, 3, v1
	v_lshlrev_b32_e32 v1, 3, v1
	s_movk_i32 s11, 0x90
	s_add_i32 s10, s5, 0xffffff80
	v_and_b32_e32 v4, 56, v1
	v_mul_lo_u32 v1, v0, s11
	s_add_u32 s6, s6, 0x7c00000
	v_add_u32_e32 v6, 0, v1
	s_movk_i32 s11, 0xff72
	s_addc_u32 s7, s7, 0
	v_lshl_add_u32 v2, v4, 1, v6
	v_mad_u64_u32 v[6:7], s[12:13], v0, s11, v[6:7]
	s_add_u32 s8, s8, 0x1cc00000
	v_mul_u32_u24_e32 v3, 0x90, v4
	v_readlane_b32 s13, v255, 26
	s_addc_u32 s9, s9, 0
	v_ashrrev_i32_e32 v1, 31, v0
	s_lshl_b32 s11, s13, 6
	s_lshl_b32 s12, s10, 6
	v_lshlrev_b32_e32 v184, 1, v4
	v_add_u32_e32 v3, v6, v3

; #define RP(bit) for (int rp_ = 0; rp_ < (((REP >> (bit)) & 1) ? 2 : 1); ++rp_)
; #define TIDX tid_opaque()
; __device__ void ya_transpose_phase(unsigned char* smem, int first_wg, int n_wg) {
;     bf16_t* tile = (bf16_t*)smem;
;     const bf16_t* yaT = (const bf16_t*)(((unsigned char*)ldp(38)) + OFF_A); bf16_t* ya = (bf16_t*)(((unsigned char*)ldp(38)) + OFF_YA);
;     const int tid = TIDX;
;     const int ntile = (MT / 64) * (HYW / 64);
;     for (int t = (int)blockIdx.x - first_wg; t < ntile; t += n_wg) {
;         const int cblk = t % (HYW / 64), rblk = t / (HYW / 64); const int b = rblk >> 5, t0 = (rblk & 31) * 64, c0 = cblk * 64;
;         __syncthreads();
;         { const int cc = tid >> 3, t8 = tid & 7; *(u32x4*)(tile + cc * 72 + t8 * 8) = *(const u32x4*)(yaT + ((size_t)(c0 + cc) * NB + b) * SEQ + t0 + t8 * 8); }
; __global__ void __launch_bounds__(512, 2) fwd_megakernel(Params p) {
;     ...
;         case 10: if (gridDim.x >= 256 && blockIdx.x >= 128) ya_transpose_phase(smem, 128, (int)gridDim.x - 128); else { if (gridDim.x < 256) ya_transpose_phase(smem, 0, (int)gridDim.x); RP(13) rg_scan_phase(smem, p); } break;
.LBB0_161:
	s_andn2_b64 vcc, exec, s[6:7]
	s_cbranch_vccnz .LBB0_183
	s_andn2_b64 vcc, exec, s[0:1]
	s_cbranch_vccnz .LBB0_166
	s_cmp_lg_u32 s40, -1
	s_cselect_b32 s0, s40, 0
	s_cselect_b32 s1, s41, 0
	s_waitcnt vmcnt(3)
	v_mov_b64_e32 v[0:1], s[0:1]
	ds_read_b64 v[2:3], v0
	s_waitcnt vmcnt(0) lgkmcnt(0)
	ds_read_b64 v[4:5], v0
	s_waitcnt vmcnt(0) lgkmcnt(0)
	v_readlane_b32 s0, v254, 34
	v_readlane_b32 s1, v254, 35
	v_mov_b32_e32 v1, v234
	s_andn2_b64 vcc, exec, s[0:1]
	s_waitcnt lgkmcnt(0)
	v_readfirstlane_b32 s1, v3
	v_readfirstlane_b32 s0, v2
	v_readfirstlane_b32 s7, v5
	v_readfirstlane_b32 s6, v4
	s_cbranch_vccnz .LBB0_166
	v_ashrrev_i32_e32 v0, 3, v1
	v_lshlrev_b32_e32 v1, 3, v1
	s_movk_i32 s8, 0x90
	s_add_u32 s0, s0, 0x7c00000
	v_and_b32_e32 v4, 56, v1
	v_mul_lo_u32 v1, v0, s8
	s_addc_u32 s1, s1, 0
	v_add_u32_e32 v6, 0, v1
	s_movk_i32 s8, 0xff72
	s_add_u32 s6, s6, 0x1cc00000
	v_lshl_add_u32 v2, v4, 1, v6
	v_mad_u64_u32 v[6:7], s[8:9], v0, s8, v[6:7]
	v_mul_u32_u24_e32 v3, 0x90, v4
	s_addc_u32 s7, s7, 0
	v_ashrrev_i32_e32 v1, 31, v0
	s_lshl_b32 s8, s5, 6
	v_lshlrev_b32_e32 v184, 1, v4
	v_add_u32_e32 v3, v6, v3
	v_readlane_b32 s9, v255, 19
	s_mov_b32 s10, s2

; #define TIDX tid_opaque()
; __device__ void rg_scan_phase(unsigned char* smem, const Params& p) {
;     float* carr = (float*)smem;
;     unsigned char* ws = (unsigned char*)ldp(38);
;     const bf16_t* loga = (const bf16_t*)(ws + OFF_B); const bf16_t* uu = (const bf16_t*)(ws + OFF_B + 64 * MiB);
;     const bf16_t* urg = (const bf16_t*)(ws + OFF_A + 96 * MiB); bf16_t* yc = (bf16_t*)(ws + OFF_YA); bf16_t* hfb = (bf16_t*)(ws + OFF_XC);
;     const int tid = TIDX, cp = tid & 31, seg = tid >> 5;
;     for (int tile = blockIdx.x; tile < NB * 8; tile += gridDim.x) {
;         const int b = tile >> 3, j = (tile & 7) * 64 + 2 * cp;
;         const size_t base = ((size_t)b * SEQ + seg * 128) * 512 + j;
.LBB0_166:
	s_cmp_lg_u32 s40, -1
	s_cselect_b32 s0, s40, 0
	s_cselect_b32 s1, s41, 0
	s_waitcnt vmcnt(3)
	v_mov_b32_e32 v0, s0
	v_mov_b32_e32 v1, s1
	ds_read_b64 v[2:3], v0
	s_waitcnt vmcnt(0) lgkmcnt(0)
	v_readlane_b32 s0, v254, 36
	v_readlane_b32 s1, v254, 37
	v_mov_b32_e32 v0, v234
	s_andn2_b64 vcc, exec, s[0:1]
	s_waitcnt lgkmcnt(0)
	v_readfirstlane_b32 s7, v3
	v_readfirstlane_b32 s6, v2
	s_cbranch_vccnz .LBB0_183
	v_lshlrev_b32_e32 v1, 1, v0
	v_and_b32_e32 v33, 62, v1
	v_ashrrev_i32_e32 v32, 5, v0
	v_lshlrev_b32_e32 v4, 3, v33
	v_lshlrev_b32_e32 v1, 9, v32
	v_add_u32_e32 v34, 0, v4
	v_lshlrev_b32_e32 v2, 7, v32
	v_add_u32_e32 v35, v34, v1
	v_or_b32_e32 v1, v1, v4
	v_ashrrev_i32_e32 v3, 31, v2
	v_add_u32_e32 v1, 0x2000, v1
	v_and_b32_e32 v0, 31, v0
	v_readlane_b32 s0, v255, 28
	v_cmp_lt_i32_e64 s[8:9], 0, v32
	v_cmp_gt_i32_e64 s[10:11], 15, v32
	v_lshlrev_b64 v[8:9], 9, v[2:3]
	s_lshl_b32 s20, s5, 6
	v_lshl_add_u32 v36, v0, 4, s0
	v_mad_i64_i32 v[10:11], s[0:1], v2, s89, 0
	v_lshlrev_b64 v[12:13], 11, v[2:3]
	v_add_u32_e32 v37, 0, v1
	v_readlane_b32 s21, v255, 19
	s_mov_b32 s22, s2

; __device__ void hyena_phase(unsigned char* smem, const Params& p, int l, int order) {
;     bf16_t* zs = (bf16_t*)smem;
;     bf16_t* fs = (bf16_t*)(smem + 16 * ZS * 2);
;     unsigned char* ws = (unsigned char*)ldp(38);
;     const bf16_t* hyT = (const bf16_t*)(ws + OFF_B); bf16_t* z1T = (bf16_t*)(ws + OFF_B + 96 * MiB); bf16_t* yaT = (bf16_t*)(ws + OFF_A);
;     const bf16_t* rvp = (const bf16_t*)(ws + OFF_YA);
;     const float* skip = ((const float*)ldp(17)) + (size_t)l * 2 * HYW + order * HYW;
;     const int tid = TIDX, lane = tid & 63, w = tid >> 6, r16 = lane & 15, g4 = lane >> 4;
;     for (int c = blockIdx.x; c < HYW; c += gridDim.x) {
;         const bf16_t* zin = (order == 0) ? hyT + (size_t)c * NB * SEQ : z1T + (size_t)c * NB * SEQ;
;         const bf16_t* gin = hyT + ((size_t)(order + 1) * HYW + c) * NB * SEQ;
;         bf16_t* dst = (order == 0 ? z1T : yaT) + (size_t)c * NB * SEQ;
;         const float sk = skip[c];
;         __syncthreads();
;         { const u32x4 rw = *(const u32x4*)(rvp + ((size_t)order * 512 + c) * 4096 + tid * 8);
;           const unsigned short e[8] = {(unsigned short)(rw.x & 0xffff), (unsigned short)(rw.x >> 16), (unsigned short)(rw.y & 0xffff), (unsigned short)(rw.y >> 16),
;                                        (unsigned short)(rw.z & 0xffff), (unsigned short)(rw.z >> 16), (unsigned short)(rw.w & 0xffff), (unsigned short)(rw.w >> 16)};
; #pragma unroll
;           for (int m = 0; m < 8; ++m) {
; #pragma unroll
;               for (int k = 0; k < 8; ++k) { const int x = tid * 8 + k - m; if (x >= 0) fs[m * FS + x] = e[k]; } } }
;         for (int idx = tid; idx < 16 * 256; idx += 512) { const int b = idx >> 8, s8 = idx & 255; *(u32x4*)(zs + b * ZS + s8 * 8) = *(const u32x4*)(zin + (size_t)b * SEQ + s8 * 8); }
;         __syncthreads();
;         const int mcopy = (8 - (r16 & 7)) & 7;
;         const bf16_t* fbase = fs + mcopy * FS - mcopy + 2048 - r16 + 8 * g4;
; __global__ void __launch_bounds__(512, 2) fwd_megakernel(Params p) {
;     ...
;         case 9: d.kind = 7; d.A = (const bf16_t*)(((unsigned char*)ldp(38)) + OFF_XC); d.Bt = wt + W_RG; d.N = 2048; d.K = 512; d.q0 = ((unsigned char*)ldp(38)) + OFF_XC; d.p0 = RB; d.p1 = RB + 64 * MiB;
;                 d.q1 = ((const float*)ldp(22)) + l * 1024; d.q2 = ((const float*)ldp(24)) + l * 1024; d.q3 = (const float*)(((unsigned char*)ldp(38)) + OFF_SM) + 4224; break;
.LBB0_188:
	s_and_b64 vcc, exec, s[0:1]
	s_cbranch_vccz .LBB0_197
	s_mul_i32 s6, s91, 0xcccccccd
	s_mul_hi_u32 s7, s90, 0xcccccccd
	s_mul_hi_u32 s5, s91, 0xcccccccd
	s_add_u32 s6, s6, s7
	s_mul_i32 s1, s90, 0xcccccccc
	s_addc_u32 s5, s5, 0
	s_mul_hi_u32 s0, s90, 0xcccccccc
	s_add_u32 s1, s1, s6
	s_addc_u32 s0, s0, 0
	s_add_u32 s0, s5, s0
	s_addc_u32 s1, 0, 0
	s_mul_i32 s6, s91, 0xcccccccc
	s_mul_hi_u32 s5, s91, 0xcccccccc
	s_add_u32 s0, s6, s0
	s_addc_u32 s1, s5, s1
	s_lshr_b64 s[0:1], s[0:1], 4
	v_writelane_b32 v255, s0, 52
	s_cmp_gt_i32 s27, 3
	s_nop 0
	v_writelane_b32 v255, s1, 53
	s_mov_b64 s[0:1], -1
	s_cbranch_scc0 .LBB0_290
	v_writelane_b32 v255, s0, 54
	s_cmp_lt_i32 s27, 6
	s_mov_b64 s[8:9], -1
	v_writelane_b32 v255, s1, 55
	s_cbranch_scc1 .LBB0_276
	s_cmp_lt_i32 s27, 7
	s_mov_b64 s[0:1], -1
	s_cbranch_scc1 .LBB0_242
	s_mov_b64 s[6:7], -1
	s_cmp_gt_i32 s27, 8
	s_cbranch_scc0 .LBB0_194
	s_cmp_lg_u32 s40, -1
	s_cselect_b32 s0, s40, 0
	s_cselect_b32 s1, s41, 0
	s_waitcnt vmcnt(3)
	v_mov_b64_e32 v[0:1], s[0:1]
	ds_read_b64 v[2:3], v0
	s_waitcnt vmcnt(0) lgkmcnt(0)
	ds_read_b64 v[4:5], v0
	s_waitcnt vmcnt(0) lgkmcnt(0)
	v_readfirstlane_b32 s1, v2
	v_readfirstlane_b32 s0, v3
	s_add_u32 s28, s1, 0x1ac00000
	v_readfirstlane_b32 s8, v4
	s_addc_u32 s29, s0, 0
	v_readfirstlane_b32 s5, v5
	s_add_u32 s42, s8, 0x1ac00000
	s_addc_u32 s43, s5, 0
	s_add_i32 s0, 0, 0x23eb0
	s_cmp_lg_u32 s0, -1
	s_cselect_b32 s0, s0, 0
	s_cselect_b32 s1, s41, 0
	v_mov_b32_e32 v2, s0
	v_mov_b32_e32 v3, s1
	ds_read_b64 v[2:3], v2
	s_waitcnt vmcnt(0) lgkmcnt(0)
	s_lshl_b32 s0, s30, 12
	s_waitcnt lgkmcnt(0)
	v_readfirstlane_b32 s5, v2
	v_readfirstlane_b32 s1, v3
	s_add_u32 s72, s5, s0
	s_addc_u32 s73, s1, 0
	s_add_i32 s1, 0, 0x23ec0
	s_cmp_lg_u32 s1, -1
	s_cselect_b32 s1, s1, 0
	s_cselect_b32 s5, s41, 0
	v_mov_b32_e32 v2, s1
	v_mov_b32_e32 v3, s5
	ds_read_b64 v[2:3], v2
	s_waitcnt vmcnt(0) lgkmcnt(0)
	ds_read_b64 v[0:1], v0
	s_waitcnt vmcnt(0) lgkmcnt(0)
	v_readfirstlane_b32 s5, v2
	v_readfirstlane_b32 s1, v3
	s_add_u32 s56, s5, s0
	v_readfirstlane_b32 s9, v0
	s_addc_u32 s57, s1, 0
	v_readfirstlane_b32 s8, v1
	s_add_u32 s20, s9, 0x22c04200
	s_addc_u32 s21, s8, 0
	s_mov_b64 s[0:1], 0
.LBB0_194:
	s_andn2_b64 vcc, exec, s[0:1]
	s_cbranch_vccnz .LBB0_241
	s_cmp_lg_u32 s40, -1
	s_cselect_b32 s0, s40, 0
	s_cselect_b32 s1, s41, 0
	s_waitcnt vmcnt(3)
	v_mov_b32_e32 v0, s0
	s_add_i32 s0, 0, 0x23e88
	s_cmp_lg_u32 s0, -1
	v_mov_b32_e32 v1, s1
	s_cselect_b32 s0, s0, 0
	s_cselect_b32 s1, s41, 0
	v_mov_b32_e32 v2, s0
	v_mov_b32_e32 v3, s1
	ds_read_b64 v[0:1], v0
	s_waitcnt vmcnt(0) lgkmcnt(0)
	v_readlane_b32 s0, v254, 44
	ds_read_b64 v[2:3], v2
	s_waitcnt vmcnt(0) lgkmcnt(0)
	v_readlane_b32 s1, v254, 45
	v_mov_b32_e32 v106, v234
	s_andn2_b64 vcc, exec, s[0:1]
	s_waitcnt lgkmcnt(0)
	v_readfirstlane_b32 s0, v1
	v_readfirstlane_b32 s1, v0
	v_readfirstlane_b32 s5, v3
	v_readfirstlane_b32 s6, v2
	s_cbranch_vccnz .LBB0_816
	s_add_i32 s8, s27, -7
	s_and_b32 s7, 0xffff, s30
	s_lshl_b32 s7, s7, 12
	s_lshl_b32 s24, s8, 9
	s_add_u32 s9, s6, s7
	s_addc_u32 s10, s5, 0
	s_lshl_b64 s[6:7], s[24:25], 2
	s_add_u32 s5, s9, s6
	s_addc_u32 s14, s10, s7
	s_add_u32 s12, s1, 0x18c00000
	s_addc_u32 s13, s0, 0
	s_add_u32 s16, s1, 0x12c00000
	s_addc_u32 s15, s0, 0
	s_mov_b32 s9, s25
	s_add_i32 s24, s27, -6
	s_lshl_b64 s[6:7], s[8:9], 22
	s_lshl_b64 s[10:11], s[24:25], 25
	s_add_u32 s10, s16, s10
	s_addc_u32 s11, s15, s11
	s_add_u32 s6, s1, s6
	v_lshlrev_b32_e32 v88, 3, v106
	s_addc_u32 s7, s0, s7
	v_ashrrev_i32_e32 v89, 31, v88
	v_lshl_add_u64 v[0:1], v[88:89], 1, s[6:7]
	s_mov_b64 s[6:7], 0x1cc00000
	v_bfe_u32 v2, v106, 4, 2
	v_and_b32_e32 v3, 15, v106
	v_lshl_add_u64 v[90:91], v[0:1], 0, s[6:7]
	s_movk_i32 s6, 0x1010
	v_lshlrev_b32_e32 v1, 2, v106
	v_lshlrev_b32_e32 v7, 4, v2
	v_mad_u32_u24 v8, v3, s6, 0
	v_and_b32_e32 v9, 0xffffff00, v1
	v_lshlrev_b32_e32 v1, 2, v2
	v_lshlrev_b32_e32 v2, 4, v106
	v_readlane_b32 s6, v255, 30
	v_sub_u32_e32 v0, 0, v106
	v_readlane_b32 s7, v255, 29
	v_add_u32_e32 v108, s6, v2
	v_readlane_b32 s6, v255, 31
	v_and_b32_e32 v4, 7, v0
	v_mov_b32_e32 v0, s7
	v_add_u32_e32 v110, s6, v2
	v_readlane_b32 s6, v255, 32
	s_movk_i32 s18, 0x2010
	v_mad_u32_u24 v0, v4, s18, v0
	v_add_u32_e32 v112, s6, v2
	v_readlane_b32 s6, v255, 33
	v_lshlrev_b32_e32 v5, 1, v4
	v_sub_u32_e32 v0, v0, v5
	v_add_u32_e32 v115, s6, v2
	v_readlane_b32 s6, v255, 34
	v_lshlrev_b32_e32 v6, 1, v3
	s_cmp_eq_u32 s8, 0
	v_add_u32_e32 v117, s6, v2
	v_readlane_b32 s6, v255, 35
	s_mov_b32 s8, 0x18c00000
	v_sub_u32_e32 v0, v0, v6
	v_add_u32_e32 v120, s6, v2
	v_readlane_b32 s6, v255, 36
	v_mad_u32_u24 v4, v4, s18, v7
	s_cselect_b32 s17, s8, 0x7c00000
	v_add_u32_e32 v0, v0, v7
	v_add_u32_e32 v107, s7, v2
	v_add_u32_e32 v123, s6, v2
	v_lshlrev_b32_e32 v2, 1, v9
	v_sub_u32_e32 v4, v4, v5
	v_sub_u32_e32 v126, v0, v2
	v_or_b32_e32 v0, v1, v9
	s_cselect_b32 s15, s15, s13
	s_cselect_b32 s22, s16, s12
	s_add_u32 s6, s1, s17
	v_sub_u32_e32 v4, v4, v6
	v_and_b32_e32 v5, 0xfffffe00, v88
	v_lshlrev_b32_e32 v184, 12, v3
	v_ashrrev_i32_e32 v1, 31, v0
	s_addc_u32 s7, s0, 0
	v_ashrrev_i32_e32 v3, 31, v9
	v_mov_b32_e32 v2, v0
	v_sub_u32_e32 v4, v4, v5
	v_cmp_gt_i32_e32 vcc, s78, v106
	v_add_u32_e32 v89, v8, v7
	v_lshl_add_u64 v[92:93], s[10:11], 0, v[184:185]
	v_cmp_lt_i32_e64 s[8:9], -1, v106
	v_cmp_lt_i32_e64 s[10:11], 0, v106
	v_add_u32_e32 v109, -2, v108
	v_add_u32_e32 v111, -4, v110
	v_add_u32_e32 v113, -6, v112
	v_add_u32_e32 v114, -2, v112
	v_add_u32_e32 v116, -8, v115
	v_add_u32_e32 v118, -10, v117
	v_add_u32_e32 v119, -2, v117
	v_add_u32_e32 v121, -12, v120
	v_add_u32_e32 v122, -4, v120
	v_add_u32_e32 v124, -14, v123
	v_add_u32_e32 v125, -2, v123
	v_lshl_add_u32 v127, v0, 1, v8
	v_lshl_add_u64 v[94:95], s[6:7], 0, v[184:185]
	v_add_u32_e32 v128, 0, v4
	v_lshlrev_b64 v[96:97], 1, v[0:1]
	v_lshlrev_b64 v[98:99], 1, v[2:3]
	s_mov_b32 s6, s2
	s_branch .LBB0_199

; #define TIDX tid_opaque()
; __device__ void filter_finalize_phase() {
;     unsigned char* ws = (unsigned char*)ldp(38);
;     const float* hraw = (const float*)(ws + OFF_A + 160 * MiB); const float* norms = (const float*)(ws + OFF_SM); bf16_t* rv = (bf16_t*)(ws + OFF_YA);
;     const int tid = TIDX, lane = tid & 63, gw = blockIdx.x * 8 + (tid >> 6), nw = gridDim.x * 8;
;     for (int oc = gw; oc < 1024; oc += nw) {
;         const int o = oc >> 9, c = oc & 511;
;         float ns = norms[16384 + lane * 2048 + o * 512 + c] + norms[16384 + lane * 2048 + (2 + o) * 512 + c];
; #pragma unroll
;         for (int sft = 32; sft >= 1; sft >>= 1) ns += __shfl_xor(ns, sft);
;         const float scale = 1.0f / (ns + 1e-6f);
;         const float* kf = hraw + ((size_t)(0 * 2 + o) * 512 + c) * 2048; const float* kb = hraw + ((size_t)(1 * 2 + o) * 512 + c) * 2048;
;         for (int it = 0; it < 8; ++it) { const int i0 = it * 512 + lane * 8; float v[8];
.LBB0_243:
	s_cmp_lg_u32 s40, -1
	s_cselect_b32 s0, s40, 0
	s_cselect_b32 s1, s41, 0
	s_waitcnt vmcnt(3)
	v_mov_b32_e32 v0, s0
	v_mov_b32_e32 v1, s1
	ds_read_b64 v[2:3], v0
	s_waitcnt vmcnt(0) lgkmcnt(0)
	v_readlane_b32 s0, v254, 19
	v_mov_b32_e32 v1, v234
	v_readlane_b32 s1, v254, 20
	s_load_dword s14, s[0:1], 0x0
	v_ashrrev_i32_e32 v0, 6, v1
	v_add_u32_e32 v0, s77, v0
	s_movk_i32 s0, 0x400
	v_cmp_gt_i32_e32 vcc, s0, v0
	s_waitcnt lgkmcnt(0)
	v_readfirstlane_b32 s19, v3
	v_readfirstlane_b32 s18, v2
	s_and_saveexec_b64 s[6:7], vcc
	s_cbranch_execz .LBB0_248
	v_and_b32_e32 v7, 63, v1
	v_mov_b32_e32 v1, 0x4000
	v_lshl_add_u32 v33, v7, 11, v1
	v_and_b32_e32 v1, 64, v243
	v_add_u32_e32 v1, 64, v1
	v_xor_b32_e32 v2, 32, v243
	v_cmp_lt_i32_e32 vcc, v2, v1
	v_lshlrev_b32_e32 v24, 3, v7
	s_add_u32 s10, s18, 0x11c00000
	v_cndmask_b32_e32 v2, v243, v2, vcc
	v_lshlrev_b32_e32 v40, 2, v2
	v_xor_b32_e32 v2, 16, v243
	v_cmp_lt_i32_e32 vcc, v2, v1
	s_addc_u32 s11, s19, 0
	s_add_u32 s12, s18, 0x22c00000
	v_cndmask_b32_e32 v2, v243, v2, vcc
	v_lshlrev_b32_e32 v41, 2, v2
	v_xor_b32_e32 v2, 8, v243
	v_cmp_lt_i32_e32 vcc, v2, v1
	s_addc_u32 s13, s19, 0
	s_lshl_b32 s16, s14, 3
	v_cndmask_b32_e32 v2, v243, v2, vcc
	v_lshlrev_b32_e32 v42, 2, v2
	v_xor_b32_e32 v2, 4, v243
	v_cmp_lt_i32_e32 vcc, v2, v1
	v_sub_u32_e32 v6, 0x800, v24
	v_xor_b32_e32 v8, 0x7ff, v24
	v_cndmask_b32_e32 v2, v243, v2, vcc
	v_lshlrev_b32_e32 v43, 2, v2
	v_xor_b32_e32 v2, 2, v243
	v_cmp_lt_i32_e32 vcc, v2, v1
	v_xor_b32_e32 v10, 0x7f9, v24
	v_xor_b32_e32 v12, 0x5f9, v24
	v_cndmask_b32_e32 v2, v243, v2, vcc
	v_lshlrev_b32_e32 v44, 2, v2
	v_xor_b32_e32 v2, 1, v243
	v_cmp_lt_i32_e32 vcc, v2, v1
	v_xor_b32_e32 v16, 0x3f9, v24
	v_xor_b32_e32 v20, 0x1f9, v24
	v_cndmask_b32_e32 v1, v243, v2, vcc
	v_lshlrev_b32_e32 v45, 2, v1
	v_or_b32_e32 v1, 0x400, v24
	v_sub_u32_e32 v14, 0x800, v1
	v_or_b32_e32 v1, 0x600, v24
	v_sub_u32_e32 v18, 0x800, v1
	v_ashrrev_i32_e32 v1, 31, v0
	v_lshlrev_b64 v[4:5], 13, v[0:1]
	v_lshl_or_b32 v4, v7, 4, v4
	v_or_b32_e32 v22, 0x800, v24
	v_or_b32_e32 v26, 0xa00, v24
	v_or_b32_e32 v28, 0xc00, v24
	v_or_b32_e32 v30, 0xe00, v24
	v_lshl_add_u64 v[4:5], s[18:19], 0, v[4:5]
	s_mov_b64 s[18:19], 0x1cc01c00
	s_ashr_i32 s17, s16, 31
	v_cmp_eq_u32_e64 s[0:1], 0, v7
	v_cmp_ne_u32_e64 s[8:9], 0, v7
	v_xor_b32_e32 v2, 0x1f8, v24
	v_mov_b32_e32 v3, v185
	v_lshl_add_u64 v[4:5], v[4:5], 0, s[18:19]
	s_lshl_b64 s[18:19], s[16:17], 13
	s_mov_b64 s[20:21], 0
	v_lshlrev_b32_e32 v6, 2, v6
	v_lshlrev_b32_e32 v8, 2, v8
	v_lshlrev_b32_e32 v10, 2, v10
	v_lshlrev_b32_e32 v12, 2, v12
	v_lshlrev_b32_e32 v14, 2, v14
	v_lshlrev_b32_e32 v16, 2, v16
	v_lshlrev_b32_e32 v18, 2, v18
	v_lshlrev_b32_e32 v20, 2, v20
	v_lshlrev_b32_e32 v22, 2, v22
	v_lshlrev_b32_e32 v24, 2, v24
	v_lshlrev_b32_e32 v26, 2, v26
	v_lshlrev_b32_e32 v28, 2, v28
	v_lshlrev_b32_e32 v30, 2, v30
	s_branch .LBB0_246

; #define TIDX tid_opaque()
; __device__ __forceinline__ u32x4 zero4() { unsigned z = 0; asm volatile("" : "+v"(z)); return (u32x4){z, z, z, z}; }
; __device__ __forceinline__ float lo_bf(unsigned w) { return __uint_as_float(w << 16); }
; __device__ __forceinline__ float hi_bf(unsigned w) { return __uint_as_float(w & 0xffff0000u); }
; __device__ void hy_transpose_phase(unsigned char* smem, const Params& p, int l) {
;     float* tile = (float*)smem;
;     const bf16_t* uhy = (const bf16_t*)(((unsigned char*)ldp(38)) + OFF_A); bf16_t* hyT = (bf16_t*)(((unsigned char*)ldp(38)) + OFF_B);
;     const float* cw = ((const float*)ldp(7)) + (size_t)l * 3 * HYC; const float* cb = ((const float*)ldp(8)) + (size_t)l * HYC;
;     const int tid = TIDX;
;     const int ntile = (MT / 64) * (HYC / 64);
;     for (int t = blockIdx.x; t < ntile; t += gridDim.x) {
;         const int cblk = t % (HYC / 64), rblk = t / (HYC / 64); const int b = rblk >> 5, t0 = (rblk & 31) * 64, c0 = cblk * 64;
;         __syncthreads();
;         for (int e = tid; e < 66 * 8; e += 512) { const int rr = e >> 3, c8 = e & 7; const int tt = t0 - 1 + rr;
;             u32x4 v = zero4();
;             if (tt >= 0 && tt < SEQ) v = *(const u32x4*)(uhy + ((size_t)b * SEQ + tt) * HYC + c0 + c8 * 8);
;             float* d = tile + rr * 65 + c8 * 8;
;             d[0] = lo_bf(v.x); d[1] = hi_bf(v.x); d[2] = lo_bf(v.y); d[3] = hi_bf(v.y); d[4] = lo_bf(v.z); d[5] = hi_bf(v.z); d[6] = lo_bf(v.w); d[7] = hi_bf(v.w); }
.LBB0_248:
	s_or_b64 exec, exec, s[6:7]
	s_and_b32 s5, s30, 0xffff
	s_cmp_lg_u32 s40, -1
	s_cselect_b32 s0, s40, 0
	s_cselect_b32 s1, s41, 0
	v_mov_b64_e32 v[0:1], s[0:1]
	s_add_i32 s0, 0, 0x23e38
	s_cmp_lg_u32 s0, -1
	s_cselect_b32 s0, s0, 0
	s_cselect_b32 s1, s41, 0
	v_mov_b32_e32 v4, s0
	s_add_i32 s0, 0, 0x23e40
	s_cmp_lg_u32 s0, -1
	v_mov_b32_e32 v5, s1
	s_cselect_b32 s0, s0, 0
	s_cselect_b32 s1, s41, 0
	v_mov_b32_e32 v6, s0
	v_mov_b32_e32 v7, s1
	ds_read_b64 v[2:3], v0
	s_waitcnt vmcnt(0) lgkmcnt(0)
	ds_read_b64 v[0:1], v0
	s_waitcnt vmcnt(0) lgkmcnt(0)
	v_readlane_b32 s0, v254, 46
	ds_read_b64 v[4:5], v4
	s_waitcnt vmcnt(0) lgkmcnt(0)
	v_readlane_b32 s1, v254, 47
	ds_read_b64 v[8:9], v6
	s_waitcnt vmcnt(0) lgkmcnt(0)
	v_mov_b32_e32 v7, v234
	s_andn2_b64 vcc, exec, s[0:1]
	s_waitcnt lgkmcnt(0)
	v_readfirstlane_b32 s13, v3
	v_readfirstlane_b32 s12, v2
	v_readfirstlane_b32 s7, v1
	v_readfirstlane_b32 s6, v0
	v_readfirstlane_b32 s1, v5
	v_readfirstlane_b32 s8, v4
	v_readfirstlane_b32 s0, v9
	v_readfirstlane_b32 s10, v8
	s_cbranch_vccnz .LBB0_259
	s_add_u32 s6, s6, 0x12c00000
	s_mul_i32 s9, s5, 0x4800
	s_addc_u32 s7, s7, 0
	s_add_u32 s8, s8, s9
	v_and_b32_e32 v6, 7, v7
	s_mul_i32 s11, s5, 0x1800
	s_addc_u32 s9, s1, 0
	v_lshlrev_b32_e32 v0, 3, v7
	v_lshlrev_b32_e32 v184, 4, v6
	s_add_u32 s10, s10, s11
	v_ashrrev_i32_e32 v10, 3, v7
	v_and_b32_e32 v0, 56, v0
	v_lshl_add_u64 v[2:3], s[12:13], 0, v[184:185]
	s_mov_b64 s[12:13], 0x7c00000
	s_addc_u32 s11, s0, 0
	s_movk_i32 s0, 0x20f
	v_lshl_add_u32 v1, v10, 2, 0
	v_lshl_add_u64 v[4:5], v[2:3], 0, s[12:13]
	v_mul_u32_u24_e32 v2, 0x104, v0
	v_cmp_lt_i32_e64 s[0:1], s0, v7
	v_lshl_add_u32 v6, v6, 5, 0
	v_add_u32_e32 v11, v1, v2
	v_lshlrev_b32_e32 v184, 1, v0
	s_mov_b32 s15, s2
	v_readfirstlane_b32 s31, v7
	v_add_u32_e32 v66, 0x4400, v11
	s_mov_b32 s98, s2
	s_mul_hi_i32 s99, s98, 0x2aaaaaab
	s_lshr_b32 s100, s99, 31
	s_ashr_i32 s99, s99, 2
	s_add_i32 s99, s99, s100
	s_mul_i32 s100, s99, 24
	s_sub_i32 s100, s98, s100
	s_lshl_b32 s100, s100, 7
	s_lshl_b32 s101, s99, 6
	s_and_b32 s101, s101, 0x7c0
	s_add_i32 s101, s101, -1
	s_ashr_i32 s99, s99, 5
	s_lshl_b32 s99, s99, 11
	v_add_u32_e32 v44, s101, v10
	v_add_u32_e32 v45, s99, v44
	v_mul_u32_u24_e32 v45, 0xc00, v45
	v_add_u32_e32 v46, s100, v45
	v_mov_b32_e32 v47, 0
	v_mov_b32_e32 v36, 0
	v_mov_b32_e32 v37, 0
	v_mov_b32_e32 v38, 0
	v_mov_b32_e32 v39, 0
	v_lshl_add_u64 v[46:47], v[4:5], 0, v[46:47]
	v_cmp_gt_u32_e32 vcc, 0x800, v44
	s_and_saveexec_b64 s[28:29], vcc
	global_load_dwordx4 v[36:39], v[46:47], off
	s_mov_b64 exec, s[28:29]
	s_cmp_lt_u32 s31, 64
	s_cbranch_scc0 .Lhy3_p2_pa
	v_add_u32_e32 v44, 64, v44
	v_add_u32_e32 v45, s99, v44
	v_mul_u32_u24_e32 v45, 0xc00, v45
	v_add_u32_e32 v46, s100, v45
	v_mov_b32_e32 v47, 0
	v_mov_b32_e32 v40, 0
	v_mov_b32_e32 v41, 0
	v_mov_b32_e32 v42, 0
	v_mov_b32_e32 v43, 0
	v_lshl_add_u64 v[46:47], v[4:5], 0, v[46:47]
	v_cmp_gt_u32_e32 vcc, 0x800, v44
	v_cmp_gt_u32_e64 s[34:35], 16, v7
	s_and_b64 vcc, vcc, s[34:35]
	s_and_saveexec_b64 s[28:29], vcc
	global_load_dwordx4 v[40:43], v[46:47], off
	s_mov_b64 exec, s[28:29]

; #define TIDX tid_opaque()
; __device__ void rg_conv_phase(const Params& p, int l) {
;     const bf16_t* urg = (const bf16_t*)(((unsigned char*)ldp(38)) + OFF_A + 96 * MiB); bf16_t* xc = (bf16_t*)(((unsigned char*)ldp(38)) + OFF_XC);
;     const float* cw = ((const float*)ldp(19)) + (size_t)l * 4 * RGW; const float* cb = ((const float*)ldp(20)) + (size_t)l * RGW;
;     const int total = (MT / 16) * 64;
;     for (int idx = blockIdx.x * 512 + TIDX; idx < total; idx += gridDim.x * 512) {
;         const int c8 = idx & 63, run = idx >> 6, tok0 = run * 16, t0 = tok0 & (SEQ - 1);
.LBB0_259:
	s_cmp_lg_u32 s40, -1
	s_cselect_b32 s0, s40, 0
	s_cselect_b32 s1, s41, 0
	v_mov_b64_e32 v[0:1], s[0:1]
	s_add_i32 s0, 0, 0x23e98
	s_cmp_lg_u32 s0, -1
	s_cselect_b32 s0, s0, 0
	ds_read_b64 v[2:3], v0
	s_waitcnt vmcnt(0) lgkmcnt(0)
	ds_read_b64 v[4:5], v0
	s_waitcnt vmcnt(0) lgkmcnt(0)
	s_cselect_b32 s1, s41, 0
	v_mov_b32_e32 v0, s0
	s_add_i32 s0, 0, 0x23ea0
	s_cmp_lg_u32 s0, -1
	v_mov_b32_e32 v1, s1
	s_cselect_b32 s0, s0, 0
	s_cselect_b32 s1, s41, 0
	ds_read_b64 v[6:7], v0
	s_waitcnt vmcnt(0) lgkmcnt(0)
	v_mov_b32_e32 v0, s0
	v_mov_b32_e32 v1, s1
	ds_read_b64 v[8:9], v0
	s_waitcnt vmcnt(0) lgkmcnt(0)
	v_mov_b32_e32 v0, v234
	v_readlane_b32 s1, v254, 18
	s_mov_b32 s0, 0x20000
	s_waitcnt lgkmcnt(0)
	v_readfirstlane_b32 s7, v3
	v_add_u32_e32 v72, s1, v0
	v_readfirstlane_b32 s6, v2
	v_readfirstlane_b32 s9, v5
	v_readfirstlane_b32 s8, v4
	v_cmp_gt_i32_e32 vcc, s0, v72
	v_readfirstlane_b32 s11, v7
	v_readfirstlane_b32 s10, v6
	v_readfirstlane_b32 s13, v9
	v_readfirstlane_b32 s12, v8
	s_and_saveexec_b64 s[0:1], vcc
	s_cbranch_execz .LBB0_274
	s_lshl_b32 s15, s5, 13
	s_lshl_b32 s5, s5, 11
	s_add_u32 s6, s6, 0xdc00000
	s_addc_u32 s7, s7, 0
	s_add_u32 s8, s8, 0x1ac00000
	s_addc_u32 s9, s9, 0
	s_add_u32 s10, s10, s15
	s_addc_u32 s11, s11, 0
	s_add_u32 s12, s12, s5
	v_readlane_b32 s15, v255, 18
	s_addc_u32 s13, s13, 0
	s_lshl_b32 s5, s14, 9
	v_lshl_add_u32 v73, v0, 3, s15
	s_lshl_b32 s14, s14, 12
	s_mov_b64 s[16:17], 0
	s_branch .LBB0_262

; #define TIDX tid_opaque()
; __device__ void filter_phase(unsigned char* smem, const Params& p, int l) {
;     float* h3 = (float*)smem;
;     const float* wout = ((const float*)ldp(16)) + (size_t)l * 64 * 2048; const float* hdn = (const float*)(((unsigned char*)ldp(38)) + OFF_HDN);
;     float* hraw = (float*)(((unsigned char*)ldp(38)) + OFF_A + 160 * MiB); float* norms = (float*)(((unsigned char*)ldp(38)) + OFF_SM);
;     const int tid = TIDX;
;     for (int tile = blockIdx.x; tile < 256; tile += gridDim.x) {
;         const int cb = tile & 3, pb = tile >> 2;
;         __syncthreads();
;         ((f32x4*)h3)[tid] = ((const f32x4*)(hdn + (size_t)pb * 32 * 64))[tid];
;         __syncthreads();
;         const int c = tid, dir = cb >> 1, o = cb & 1;
;         const float da = -4.605170185988091f / 0.3f, db = -4.605170185988091f / 1.5f; const float delta = fabsf(da + (float)c * ((db - da) / 511.0f));
;         float asum = 0.f; float* dst = hraw + ((size_t)(dir * 2 + o) * 512 + c) * 2048 + pb * 32;
.LBB0_276:
	s_mov_b32 s11, 0
	v_writelane_b32 v255, s11, 58
	s_andn2_b64 vcc, exec, s[8:9]
	s_mov_b64 s[8:9], 0
	v_writelane_b32 v255, s8, 56
	s_mov_b64 s[0:1], 0
	s_mov_b64 s[12:13], 0
	v_writelane_b32 v255, s9, 57
	s_cbranch_vccnz .LBB0_290
	s_mov_b64 s[6:7], -1
	v_writelane_b32 v255, s6, 54
	s_cmp_gt_i32 s27, 4
	s_nop 0
	v_writelane_b32 v255, s7, 55
	s_mov_b64 s[6:7], -1
	s_cbranch_scc0 .LBB0_286
	s_add_i32 s5, 0, 0x23e80
	s_cmp_lg_u32 s5, -1
	s_cselect_b32 s5, s5, 0
	s_cselect_b32 s6, s41, 0
	s_cmp_lg_u32 s40, -1
	s_waitcnt vmcnt(3)
	v_mov_b32_e32 v0, s5
	v_mov_b32_e32 v1, s6
	s_cselect_b32 s6, s40, 0
	s_cselect_b32 s7, s41, 0
	ds_read_b64 v[2:3], v0
	s_waitcnt vmcnt(0) lgkmcnt(0)
	v_mov_b64_e32 v[0:1], s[6:7]
	ds_read_b64 v[4:5], v0
	s_waitcnt vmcnt(0) lgkmcnt(0)
	ds_read_b64 v[6:7], v0
	s_waitcnt vmcnt(0) lgkmcnt(0)
	ds_read_b64 v[8:9], v0
	s_waitcnt vmcnt(0) lgkmcnt(0)
	v_readlane_b32 s6, v254, 48
	v_readlane_b32 s7, v254, 49
	v_mov_b32_e32 v0, v234
	s_and_b64 vcc, exec, s[6:7]
	s_waitcnt lgkmcnt(0)
	v_readfirstlane_b32 s11, v5
	v_readfirstlane_b32 s12, v3
	v_readfirstlane_b32 s13, v2
	v_readfirstlane_b32 s10, v4
	v_readfirstlane_b32 s7, v7
	v_readfirstlane_b32 s6, v6
	v_readfirstlane_b32 s5, v9
	v_readfirstlane_b32 s8, v8
	s_cbranch_vccz .LBB0_285
	v_ashrrev_i32_e32 v1, 31, v0
	s_add_u32 s6, s6, 0x11c00000
	v_lshl_add_u64 v[2:3], v[0:1], 4, s[10:11]
	s_mov_b64 s[10:11], 0x22f00000
	s_addc_u32 s7, s7, 0
	v_lshl_add_u64 v[2:3], v[2:3], 0, s[10:11]
	v_readlane_b32 s10, v254, 19
	s_add_u32 s8, s8, 0x22c00000
	v_readlane_b32 s14, v255, 52
	v_readlane_b32 s11, v254, 20
	s_addc_u32 s9, s5, 0
	v_readlane_b32 s15, v255, 53
	v_cvt_f32_i32_e32 v4, v0
	s_load_dword s5, s[10:11], 0x0
	s_lshl_b64 s[14:15], s[14:15], 19
	s_add_u32 s10, s13, s14
	v_mov_b32_e32 v5, 0xc1759bec
	s_addc_u32 s11, s12, s15
	v_lshl_add_u32 v28, v0, 4, 0
	v_fmamk_f32 v29, v4, 0x3cc4df2d, v5
	v_add_u32_e32 v30, 0x4000, v0
	v_lshl_add_u64 v[4:5], v[0:1], 2, s[10:11]
	s_mov_b32 s14, s2
	s_mov_b32 s15, s2

; #define TIDX tid_opaque()
; __device__ __forceinline__ bf16_t f2bf(float f) { unsigned u = __float_as_uint(f); u += 0x7FFFu + ((u >> 16) & 1u); return (bf16_t)(u >> 16); }
;     if (ld == 0) ld = K;
;     const int tid = TIDX, lane = tid & 63, w = tid >> 6;
;     const int nkt = K / 64, ntile = (R / 64) * nkt;
;     const int first = ((int)blockIdx.x + rot) % (int)gridDim.x;
;     for (int t_ = first; t_ < ntile * ((REP & 1) + 1); t_ += gridDim.x) { const int t = t_ % ntile;
;         const int r0 = (t / nkt) * 64, k0 = (t % nkt) * 64;
;         __syncthreads();
; #pragma unroll
;         for (int i = 0; i < 8; ++i) { const int kk = i * 8 + w; tile[kk * 65 + lane] = src(k0 + kk, r0 + lane); }
;         __syncthreads();
; #pragma unroll
;         for (int i = 0; i < 8; ++i) { const int j = i * 8 + w; Bt[(size_t)(r0 + j) * ld + k0 + lane] = f2bf(tile[lane * 65 + j]); }
; __device__ void convert_phase(unsigned char* smem, const Params& p, int l) {
;     float* tile = (float*)smem; bf16_t* wt = (bf16_t*)(((unsigned char*)ldp(38)) + OFF_WT);
;     const size_t uo = (size_t)l * DM * DFF;
;     { const float* wg = ((const float*)ldp(2)) + uo; const float* wu = ((const float*)ldp(3)) + uo; const float* gn = ((const float*)ldp(1)) + l * DM;
;       conv_tiles(tile, wt + W_UP1, 5632, 1024, 0, [=](int k, int r) { const int col = (r >> 5) * 16 + (r & 15); return gn[k] * (((r >> 4) & 1) ? wu[(size_t)k * DFF + col] : wg[(size_t)k * DFF + col]); }); }
.LBB0_304:
	s_cmp_eq_u32 s27, 0
	s_cbranch_scc0 .LBB0_407
	s_cmp_lg_u32 s40, -1
	s_cselect_b32 s0, s40, 0
	s_cselect_b32 s1, s41, 0
	s_waitcnt vmcnt(3)
	v_mov_b32_e32 v0, s0
	s_and_b32 s12, s30, 0xffff
	s_add_i32 s0, 0, 0x23e10
	s_cmp_lg_u32 s0, -1
	v_mov_b32_e32 v1, s1
	s_cselect_b32 s0, s0, 0
	ds_read_b64 v[2:3], v0
	s_waitcnt vmcnt(0) lgkmcnt(0)
	s_cselect_b32 s1, s41, 0
	v_mov_b32_e32 v0, s0
	s_add_i32 s0, 0, 0x23e18
	s_cmp_lg_u32 s0, -1
	v_mov_b32_e32 v1, s1
	s_cselect_b32 s0, s0, 0
	ds_read_b64 v[4:5], v0
	s_waitcnt vmcnt(0) lgkmcnt(0)
	s_cselect_b32 s1, s41, 0
	v_mov_b32_e32 v0, s0
	s_add_i32 s0, 0, 0x23e08
	s_cmp_lg_u32 s0, -1
	v_mov_b32_e32 v1, s1
	s_cselect_b32 s0, s0, 0
	s_cselect_b32 s1, s41, 0
	ds_read_b64 v[6:7], v0
	s_waitcnt vmcnt(0) lgkmcnt(0)
	v_mov_b32_e32 v0, s0
	v_mov_b32_e32 v1, s1
	ds_read_b64 v[8:9], v0
	s_waitcnt vmcnt(0) lgkmcnt(0)
	v_readlane_b32 s0, v254, 19
	v_mov_b32_e32 v0, v234
	v_readlane_b32 s1, v254, 20
	s_load_dword s5, s[0:1], 0x0
	v_readlane_b32 s1, v255, 17
	s_lshl_b32 s10, s30, 10
	s_mul_i32 s15, s12, 0x2c0000
	s_waitcnt lgkmcnt(0)
	s_abs_i32 s13, s5
	v_cvt_f32_u32_e32 v1, s13
	s_sub_i32 s0, 0, s13
	v_rcp_iflag_f32_e32 v1, v1
	s_nop 0
	v_mul_f32_e32 v1, 0x4f7ffffe, v1
	v_cvt_u32_f32_e32 v1, v1
	v_readfirstlane_b32 s9, v5
	v_readfirstlane_b32 s14, v1
	s_mul_i32 s0, s0, s14
	s_mul_hi_u32 s0, s14, s0
	s_add_i32 s14, s14, s0
	s_mul_hi_u32 s0, s1, s14
	s_mul_i32 s0, s0, s13
	s_sub_i32 s0, s1, s0
	s_sub_i32 s1, s0, s13
	s_cmp_ge_u32 s0, s13
	s_cselect_b32 s0, s1, s0
	s_sub_i32 s1, s0, s13
	s_cmp_ge_u32 s0, s13
	s_cselect_b32 s0, s1, s0
	s_xor_b32 s0, s0, s3
	s_sub_i32 s11, s0, s3
	s_cmpk_gt_i32 s11, 0x57f
	v_readfirstlane_b32 s1, v3
	v_readfirstlane_b32 s0, v2
	v_readfirstlane_b32 s8, v4
	v_readfirstlane_b32 s17, v7
	v_readfirstlane_b32 s16, v6
	v_readfirstlane_b32 s7, v9
	v_readfirstlane_b32 s6, v8
	s_cbranch_scc1 .LBB0_308
	v_and_b32_e32 v4, 63, v0
	v_ashrrev_i32_e32 v5, 6, v0
	v_and_b32_e32 v6, 15, v0
	v_and_b32_e32 v0, 16, v0
	s_lshl_b32 s18, s10, 2
	v_mov_b32_e32 v1, s17
	v_mov_b32_e32 v2, s9
	v_cmp_eq_u32_e32 vcc, 0, v0
	s_add_u32 s6, s6, s18
	v_mov_b32_e32 v0, s16
	v_cndmask_b32_e32 v1, v1, v2, vcc
	v_mov_b32_e32 v2, s8
	s_movk_i32 s8, 0x104
	s_addc_u32 s7, s7, 0
	v_cndmask_b32_e32 v0, v0, v2, vcc
	s_lshl_b32 s24, s15, 2
	v_lshl_add_u32 v15, v4, 2, 0
	v_lshlrev_b32_e32 v7, 8, v4
	v_lshlrev_b32_e32 v184, 1, v4
	v_lshlrev_b32_e32 v8, 2, v5
	v_mul_lo_u32 v16, v5, s8
	v_lshl_add_u64 v[0:1], v[0:1], 0, s[24:25]
	v_lshl_add_u64 v[2:3], s[0:1], 0, v[184:185]
	v_add3_u32 v7, v15, v7, v8
	v_add_u32_e32 v8, 8, v5
	v_add_u32_e32 v9, 16, v5
	v_add_u32_e32 v10, 24, v5
	v_add_u32_e32 v11, 32, v5
	v_add_u32_e32 v12, 40, v5
	v_add_u32_e32 v13, 48, v5
	v_add_u32_e32 v14, 56, v5
	v_add_u32_e32 v15, v15, v16

; #define TIDX tid_opaque()
; __device__ void convert_phase(unsigned char* smem, const Params& p, int l) {
;     ...
;     float* sm = (float*)(((unsigned char*)ldp(38)) + OFF_SM);
;     if (blockIdx.x == 0) { for (int i = TIDX; i < 1024; i += 512) sm[i] = 0.0f; }
.LBB0_357:
	s_cmp_lg_u32 s40, -1
	s_cselect_b32 s0, s40, 0
	s_cselect_b32 s1, s41, 0
	v_mov_b32_e32 v0, s0
	v_mov_b32_e32 v1, s1
	ds_read_b64 v[0:1], v0
	s_waitcnt vmcnt(0) lgkmcnt(0)
	v_readlane_b32 s0, v254, 54
	v_readlane_b32 s1, v254, 55
	s_andn2_b64 vcc, exec, s[0:1]
	s_waitcnt lgkmcnt(0)
	v_readfirstlane_b32 s1, v1
	v_readfirstlane_b32 s0, v0
	s_cbranch_vccnz .LBB0_367
	v_mov_b32_e32 v0, v234
	s_movk_i32 s6, 0x400
	s_nop 0
	v_cmp_gt_i32_e32 vcc, s6, v0
	s_and_saveexec_b64 s[6:7], vcc
	s_movk_i32 s10, 0x1ff
	s_cbranch_execz .LBB0_366
	v_max_i32_e32 v1, 0x200, v0
	v_sub_u32_e32 v1, v1, v0
	s_add_u32 s8, s0, 0x22c00000
	v_add_u32_e32 v1, 0x1ff, v1
	s_addc_u32 s9, s1, 0
	v_cmp_lt_u32_e32 vcc, s10, v1
	s_mov_b64 s[12:13], -1
	s_and_saveexec_b64 s[10:11], vcc
	s_cbranch_execz .LBB0_363
	v_lshrrev_b32_e32 v1, 9, v1
	v_add_u32_e32 v4, 1, v1
	v_and_b32_e32 v5, 0xfffffe, v4
	v_add_u32_e32 v1, 0x200, v0
	s_mov_b64 s[12:13], 0
	v_mov_b32_e32 v6, v5
	v_mov_b64_e32 v[2:3], v[0:1]

; #define TIDX tid_opaque()
; __device__ void convert_phase(unsigned char* smem, const Params& p, int l) {
;     ...
;     if (blockIdx.x == 2 % gridDim.x) { const float* lam = ((const float*)ldp(25)) + l * 1024; for (int i = TIDX; i < 1024; i += 512) sm[4224 + i] = -8.0f * log1pf(expf(-lam[i])); }
.LBB0_367:
	v_cvt_f32_u32_e32 v0, s5
	s_sub_i32 s6, 0, s5
	v_rcp_iflag_f32_e32 v0, v0
	s_nop 0
	v_mul_f32_e32 v0, 0x4f7ffffe, v0
	v_cvt_u32_f32_e32 v0, v0
	s_nop 0
	v_readfirstlane_b32 s7, v0
	s_mul_i32 s6, s6, s7
	s_mul_hi_u32 s6, s7, s6
	s_add_i32 s7, s7, s6
	s_lshr_b32 s6, s7, 31
	s_mul_i32 s6, s6, s5
	s_sub_i32 s6, 2, s6
	s_sub_i32 s7, s6, s5
	s_cmp_ge_u32 s6, s5
	s_cselect_b32 s6, s7, s6
	s_sub_i32 s7, s6, s5
	s_cmp_ge_u32 s6, s5
	s_cselect_b32 s6, s7, s6
	s_cmp_lg_u32 s2, s6
	s_cbranch_scc1 .LBB0_372
	s_add_i32 s6, 0, 0x23ec8
	s_cmp_lg_u32 s6, -1
	s_cselect_b32 s6, s6, 0
	s_cselect_b32 s7, s41, 0
	v_mov_b32_e32 v0, s6
	v_mov_b32_e32 v1, s7
	ds_read_b64 v[2:3], v0
	s_waitcnt vmcnt(0) lgkmcnt(0)
	v_mov_b32_e32 v0, v234
	s_movk_i32 s6, 0x400
	s_waitcnt lgkmcnt(0)
	v_readfirstlane_b32 s8, v3
	v_readfirstlane_b32 s9, v2
	v_cmp_gt_i32_e32 vcc, s6, v0
	s_and_saveexec_b64 s[6:7], vcc
	s_movk_i32 s16, 0x1ff
	s_mov_b64 s[14:15], 0x800
	s_cbranch_execz .LBB0_371
	v_readlane_b32 s10, v255, 52
	v_readlane_b32 s11, v255, 53
	s_lshl_b64 s[10:11], s[10:11], 12
	v_ashrrev_i32_e32 v1, 31, v0
	v_lshlrev_b64 v[2:3], 2, v[0:1]
	s_add_u32 s10, s9, s10
	v_add_u32_e32 v4, 0xfffffe00, v0
	v_lshl_add_u64 v[0:1], s[0:1], 0, v[2:3]
	s_mov_b64 s[12:13], 0x22c04200
	s_addc_u32 s11, s8, s11
	v_lshl_add_u64 v[0:1], v[0:1], 0, s[12:13]
	v_lshl_add_u64 v[2:3], s[10:11], 0, v[2:3]
	s_mov_b64 s[8:9], 0

; #define TIDX tid_opaque()
; __device__ void convert_phase(unsigned char* smem, const Params& p, int l) {
;     ...
;     if (blockIdx.x == 1 % gridDim.x) {
;         const float* rb = ((const float*)ldp(18));
;         for (int i = TIDX; i < 24 * 129; i += 512) { const int hh = i / 129, delta = i % 129 - 64, d = 1 << (2 * (hh >> 3)); const int rel = delta * d;
;             const int n = rel < 0 ? -rel : rel; int bucket = rel > 0 ? 16 : 0;
;             if (n < 8) bucket += n; else { const float nf = (float)n; int lg = 8 + (int)(logf(nf / 8.0f) / 4.852030263919617f * 8.0f); if (lg > 15) lg = 15; bucket += lg; }
;             sm[1024 + i] = rb[bucket * 24 + hh]; }
.LBB0_372:
	s_cmp_lg_u32 s5, 1
	s_cselect_b64 s[6:7], -1, 0
	v_cndmask_b32_e64 v0, 0, 1, s[6:7]
	v_cmp_ne_u32_e32 vcc, s2, v0
	s_cbranch_vccnz .LBB0_381
	s_add_i32 s6, 0, 0x23e90
	s_cmp_lg_u32 s6, -1
	s_cselect_b32 s6, s6, 0
	s_cselect_b32 s7, s41, 0
	v_mov_b32_e32 v0, s6
	v_mov_b32_e32 v1, s7
	ds_read_b64 v[2:3], v0
	s_waitcnt vmcnt(0) lgkmcnt(0)
	v_mov_b32_e32 v0, v234
	s_movk_i32 s8, 0xc18
	s_waitcnt lgkmcnt(0)
	v_readfirstlane_b32 s7, v3
	v_readfirstlane_b32 s6, v2
	v_cmp_gt_i32_e32 vcc, s8, v0
	s_and_saveexec_b64 s[8:9], vcc
	s_cbranch_execz .LBB0_380
	v_ashrrev_i32_e32 v1, 31, v0
	v_lshl_add_u64 v[2:3], v[0:1], 2, s[0:1]
	s_mov_b64 s[0:1], 0x22c01000
	v_lshl_add_u64 v[2:3], v[2:3], 0, s[0:1]
	s_mov_b64 s[0:1], 0
	s_branch .LBB0_376

; #define TIDX tid_opaque()
; __device__ __forceinline__ unsigned cvt_pk_bf16(float lo, float hi) { const f32x2_t v = {lo, hi}; const bf16x2_t b = __builtin_convertvector(v, bf16x2_t); return __builtin_bit_cast(unsigned, b); }
; __device__ void prep_phase(const float* x, float* h, bf16_t* hb, float* part) {
;     const int tid = TIDX, lane = tid & 63, gw = blockIdx.x * 8 + (tid >> 6), nw = gridDim.x * 8;
;     for (int row = gw; row < MT; row += nw) {
;         const f32x4* pr = (const f32x4*)(x + (size_t)row * DM); float ss = 0.f;
; #pragma unroll
;         for (int j = 0; j < 4; ++j) { const f32x4 v = pr[lane + 64 * j]; ss += v[0] * v[0] + v[1] * v[1] + v[2] * v[2] + v[3] * v[3];
;             ((f32x4*)(h + (size_t)row * DM))[lane + 64 * j] = v;
;             u32x2 w; w.x = cvt_pk_bf16(v[0], v[1]); w.y = cvt_pk_bf16(v[2], v[3]); ((u32x2*)(hb + (size_t)row * DM))[lane + 64 * j] = w; }
; #pragma unroll
;         for (int o = 32; o >= 1; o >>= 1) ss += __shfl_xor(ss, o);
;         if (lane < 16) part[(size_t)row * 16 + lane] = (lane == 0) ? ss : 0.f;
.LBB0_400:
	s_cmp_gt_u32 s90, 19
	s_cbranch_scc1 .LBB0_407
	s_add_i32 s0, 0, 0x23e00
	s_cmp_lg_u32 s0, -1
	s_cselect_b32 s0, s0, 0
	s_cselect_b32 s1, s41, 0
	v_mov_b32_e32 v0, s0
	v_mov_b32_e32 v1, s1
	ds_read_b64 v[2:3], v0
	s_waitcnt vmcnt(0) lgkmcnt(0)
	v_mov_b32_e32 v1, v234
	s_mov_b32 s0, 0x8000
	v_ashrrev_i32_e32 v0, 6, v1
	v_add_u32_e32 v0, s77, v0
	v_cmp_gt_i32_e32 vcc, s0, v0
	s_waitcnt lgkmcnt(0)
	v_readfirstlane_b32 s7, v3
	v_readfirstlane_b32 s6, v2
	s_and_saveexec_b64 s[10:11], vcc
	s_cbranch_execz .LBB0_406
	v_and_b32_e32 v14, 63, v1
	v_and_b32_e32 v1, 64, v243
	v_add_u32_e32 v1, 64, v1
	v_xor_b32_e32 v2, 32, v243
	v_cmp_lt_i32_e64 s[8:9], v2, v1
	v_lshlrev_b32_e32 v184, 2, v14
	s_lshl_b32 s12, s5, 3
	v_cndmask_b32_e64 v2, v243, v2, s[8:9]
	v_lshlrev_b32_e32 v8, 2, v2
	v_xor_b32_e32 v2, 16, v243
	v_cmp_lt_i32_e64 s[8:9], v2, v1
	s_ashr_i32 s13, s12, 31
	v_cmp_gt_u32_e32 vcc, 16, v14
	v_cndmask_b32_e64 v2, v243, v2, s[8:9]
	v_lshlrev_b32_e32 v9, 2, v2
	v_xor_b32_e32 v2, 8, v243
	v_cmp_lt_i32_e64 s[8:9], v2, v1
	v_cmp_eq_u32_e64 s[0:1], 0, v14
	s_lshl_b64 s[16:17], s[12:13], 6
	v_cndmask_b32_e64 v2, v243, v2, s[8:9]
	v_lshlrev_b32_e32 v10, 2, v2
	v_xor_b32_e32 v2, 4, v243
	v_cmp_lt_i32_e64 s[8:9], v2, v1
	s_lshl_b64 s[18:19], s[12:13], 11
	s_lshl_b64 s[20:21], s[12:13], 12
	v_cndmask_b32_e64 v2, v243, v2, s[8:9]
	v_lshlrev_b32_e32 v11, 2, v2
	v_xor_b32_e32 v2, 2, v243
	v_cmp_lt_i32_e64 s[8:9], v2, v1
	s_mov_b64 s[22:23], 0
	s_nop 0
	v_cndmask_b32_e64 v2, v243, v2, s[8:9]
	v_lshlrev_b32_e32 v12, 2, v2
	v_xor_b32_e32 v2, 1, v243
	v_cmp_lt_i32_e64 s[8:9], v2, v1
	s_nop 1
	v_cndmask_b32_e64 v1, v243, v2, s[8:9]
	v_lshlrev_b32_e32 v13, 2, v1
	v_ashrrev_i32_e32 v1, 31, v0
	v_lshlrev_b64 v[2:3], 6, v[0:1]
	v_readlane_b32 s8, v254, 4
	v_lshl_add_u64 v[2:3], v[2:3], 0, v[184:185]
	v_readlane_b32 s9, v254, 5
	v_lshlrev_b64 v[4:5], 11, v[0:1]
	v_lshl_or_b32 v4, v14, 3, v4
	v_lshl_add_u64 v[2:3], s[8:9], 0, v[2:3]
	v_readlane_b32 s8, v254, 2
	v_readlane_b32 s9, v254, 3
	v_lshlrev_b64 v[6:7], 12, v[0:1]
	v_lshl_or_b32 v6, v14, 4, v6
	v_lshl_add_u64 v[4:5], s[8:9], 0, v[4:5]
	s_branch .LBB0_404

; #define LAS __attribute__((address_space(3)))
; __device__ __forceinline__ unsigned xb_ld(unsigned* p)              { return __hip_atomic_load(p, __ATOMIC_RELAXED, __HIP_MEMORY_SCOPE_AGENT); }
; __device__ __forceinline__ unsigned xb_xcc_id() { return (unsigned)__builtin_amdgcn_s_getreg((3 << 11) | 20) & 0xFu; }
; __device__ __forceinline__ void xcd_barrier_complete(unsigned* bar, unsigned x, unsigned& nloc, unsigned& nx) {
;     const unsigned G = gridDim.x * gridDim.y * gridDim.z;
;     unsigned sum, cnt, mine, sp = 0u;
;     for (;;) {
;         sum = 0u; cnt = 0u; mine = 0u;
; #pragma unroll
;         for (unsigned j = 0; j < 16; ++j) { const unsigned c = xb_ld(&bar[XB_XCNT(j)]); sum += c; cnt += (c > 0u) ? 1u : 0u; mine = (j == x) ? c : mine; }
; __device__ __forceinline__ void xcd_barrier() {
;     asm volatile("s_waitcnt vmcnt(0)" ::: "memory");
;     __syncthreads();
;     if (threadIdx.x == 0) {
;         unsigned* bar = (unsigned*)(((unsigned char*)ldp(38)) + OFF_BAR);
;         volatile LAS unsigned* st = (volatile LAS unsigned*)(LAS unsigned char*)(g_smem + LDS_BYTES - 1024);
;         const unsigned x = xb_xcc_id();
;         __builtin_amdgcn_s_waitcnt(0);
;         unsigned nloc = st[0], nx = st[1];
;         if (nloc == 0u) { xcd_barrier_complete(bar, x, nloc, nx); st[0] = nloc; st[1] = nx; }
.LBB0_767:
	v_readlane_b32 s0, v255, 54
	v_readlane_b32 s1, v255, 55
	s_andn2_b64 vcc, exec, s[0:1]
	s_mov_b32 s70, 0x7f800000
	s_cbranch_vccnz .LBB0_837
	s_mul_i32 s0, s90, 0xcd
	s_bfe_u32 s0, s0, 0x4000c
	s_mul_i32 s0, s0, 0xffffffec
	s_add_i32 s0, s0, s90
	s_cmp_eq_u32 s0, 7
	s_cbranch_scc1 .LBB0_837
	s_cmp_lg_u32 s90, 0
	s_cbranch_scc0 .LBB0_781
	s_waitcnt vmcnt(0)
	s_waitcnt lgkmcnt(0)
	s_barrier
	s_mov_b64 s[0:1], exec
	v_readlane_b32 s6, v254, 0
	v_readlane_b32 s7, v254, 1
	s_and_b64 s[6:7], s[0:1], s[6:7]
	s_mov_b64 exec, s[6:7]
	s_cbranch_execz .LBB0_824
	s_cmp_lg_u32 s40, -1
	s_cselect_b32 s5, s40, 0
	s_cselect_b32 s6, s41, 0
	s_waitcnt vmcnt(3)
	v_mov_b32_e32 v0, s5
	v_mov_b32_e32 v1, s6
	s_waitcnt vmcnt(2)
	ds_read_b64 v[4:5], v0
	s_waitcnt vmcnt(0) lgkmcnt(0)
	s_add_i32 s14, 0, 0x23c00
	v_mov_b32_e32 v0, s14
	s_getreg_b32 s5, hwreg(HW_REG_XCC_ID, 0, 4)
	s_waitcnt vmcnt(0) expcnt(0) lgkmcnt(0)
	ds_read_b32 v2, v0
	s_add_i32 s15, 0, 0x23c04
	v_mov_b32_e32 v0, s15
	ds_read_b32 v0, v0
	s_and_b32 s5, s5, 15
	s_waitcnt lgkmcnt(1)
	v_cmp_ne_u32_e32 vcc, 0, v2
	v_readfirstlane_b32 s7, v5
	v_readfirstlane_b32 s6, v4
	s_cbranch_vccnz .LBB0_787
	v_readlane_b32 s8, v254, 19
	v_readlane_b32 s9, v254, 20
	s_load_dwordx2 s[12:13], s[8:9], 0x0
	s_load_dword s11, s[8:9], 0x8
	s_add_u32 s8, s6, 0x22ca0200
	s_addc_u32 s9, s7, 0
	s_add_u32 s10, s6, 0x22ca0400
	s_waitcnt lgkmcnt(0)
	s_mul_i32 s24, s13, s12
	s_mul_i32 s24, s24, s11
	s_addc_u32 s11, s7, 0
	s_add_u32 s12, s6, 0x22ca0500
	s_addc_u32 s13, s7, 0
	s_add_u32 s16, s6, 0x22ca0600
	s_addc_u32 s17, s7, 0
	s_add_u32 s18, s6, 0x22ca0700
	s_addc_u32 s19, s7, 0
	s_add_u32 s20, s6, 0x22ca0800
	s_addc_u32 s21, s7, 0
	s_add_u32 s22, s6, 0x22ca0900
	s_addc_u32 s23, s7, 0
	s_add_u32 s28, s6, 0x22ca0a00
	s_addc_u32 s29, s7, 0
	s_add_u32 s42, s6, 0x22ca0b00
	s_addc_u32 s43, s7, 0
	s_add_u32 s44, s6, 0x22ca0c00
	s_addc_u32 s45, s7, 0
	s_add_u32 s46, s6, 0x22ca0d00
	s_addc_u32 s47, s7, 0
	s_add_u32 s48, s6, 0x22ca0e00
	s_addc_u32 s49, s7, 0
	s_add_u32 s50, s6, 0x22ca0f00
	s_addc_u32 s51, s7, 0
	s_add_u32 s52, s6, 0x22ca1000
	s_addc_u32 s53, s7, 0
	s_add_u32 s56, s6, 0x22ca1100
	s_addc_u32 s57, s7, 0
	s_add_u32 s58, s6, 0x22ca1200
	s_addc_u32 s59, s7, 0
	s_add_u32 s60, s6, 0x22ca1300
	s_addc_u32 s61, s7, 0
	s_mov_b32 s27, 1
	s_branch .LBB0_774

; #define TIDX tid_opaque()
; __device__ void rmsnorm_phase(const float* src, const float* g, float* copy_dst, bf16_t* xn, float* outf) {
;     const int lane = TIDX & 63, gw = blockIdx.x * 8 + (TIDX >> 6), nw = gridDim.x * 8;
;     f32x4 gv[4];
; #pragma unroll
;     for (int j = 0; j < 4; ++j) gv[j] = ((const f32x4*)g)[lane + 64 * j];
;     for (int row = gw; row < MT; row += nw) {
;         const f32x4* pr = (const f32x4*)(src + (size_t)row * DM); f32x4 v[4]; float ss = 0.f;
; __global__ void __launch_bounds__(512, 2) fwd_megakernel(Params p) {
;     ...
;         if (l == DEPTH) { rmsnorm_phase(h, ((const float*)ldp(36)), nullptr, nullptr, h); break; }
.LBB0_838:
	s_and_b64 vcc, exec, s[0:1]
	s_cbranch_vccz .LBB0_5
	s_add_i32 s0, 0, 0x23f20
	s_cmp_lg_u32 s0, -1
	s_cselect_b32 s0, s0, 0
	s_cselect_b32 s1, s41, 0
	s_waitcnt vmcnt(3)
	v_mov_b32_e32 v0, s0
	v_mov_b32_e32 v1, s1
	ds_read_b64 v[2:3], v0
	s_waitcnt vmcnt(0) lgkmcnt(0)
	v_mov_b32_e32 v0, v234
	v_mov_b32_e32 v1, v234
	s_mov_b32 s5, 0x8000
	v_ashrrev_i32_e32 v1, 6, v1
	v_add_u32_e32 v32, s77, v1
	v_cmp_gt_i32_e32 vcc, s5, v32
	s_waitcnt lgkmcnt(0)
	v_readfirstlane_b32 s1, v3
	v_readfirstlane_b32 s0, v2
	s_and_saveexec_b64 s[6:7], vcc
	s_cbranch_execz .LBB0_4
	v_lshlrev_b32_e32 v0, 4, v0
	v_and_b32_e32 v18, 0x3f0, v0
	s_nop 0
	global_load_dwordx4 v[0:3], v18, s[0:1]
	global_load_dwordx4 v[4:7], v18, s[0:1] offset:1024
	global_load_dwordx4 v[8:11], v18, s[0:1] offset:2048
	global_load_dwordx4 v[12:15], v18, s[0:1] offset:3072
	v_and_b32_e32 v16, 64, v243
	v_add_u32_e32 v16, 64, v16
	v_xor_b32_e32 v17, 32, v243
	v_cmp_lt_i32_e32 vcc, v17, v16
	v_readlane_b32 s0, v254, 19
	v_readlane_b32 s1, v254, 20
	v_cndmask_b32_e32 v17, v243, v17, vcc
	v_lshlrev_b32_e32 v36, 2, v17
	v_xor_b32_e32 v17, 16, v243
	v_cmp_lt_i32_e32 vcc, v17, v16
	s_load_dword s0, s[0:1], 0x0
	v_ashrrev_i32_e32 v33, 31, v32
	v_cndmask_b32_e32 v17, v243, v17, vcc
	v_lshlrev_b32_e32 v37, 2, v17
	v_xor_b32_e32 v17, 8, v243
	v_cmp_lt_i32_e32 vcc, v17, v16
	s_waitcnt lgkmcnt(0)
	s_lshl_b32 s8, s0, 3
	v_readlane_b32 s0, v255, 22
	v_cndmask_b32_e32 v17, v243, v17, vcc
	v_lshlrev_b32_e32 v38, 2, v17
	v_xor_b32_e32 v17, 4, v243
	v_cmp_lt_i32_e32 vcc, v17, v16
	v_readlane_b32 s1, v255, 23
	s_ashr_i32 s9, s8, 31
	v_cndmask_b32_e32 v17, v243, v17, vcc
	v_lshlrev_b32_e32 v39, 2, v17
	v_xor_b32_e32 v17, 2, v243
	v_cmp_lt_i32_e32 vcc, v17, v16
	s_lshl_b64 s[10:11], s[8:9], 12
	s_mov_b64 s[12:13], 0
	v_cndmask_b32_e32 v17, v243, v17, vcc
	v_lshlrev_b32_e32 v40, 2, v17
	v_xor_b32_e32 v17, 1, v243
	v_cmp_lt_i32_e32 vcc, v17, v16
	s_nop 1
	v_cndmask_b32_e32 v16, v243, v17, vcc
	v_lshlrev_b32_e32 v41, 2, v16
	v_lshlrev_b64 v[16:17], 12, v[32:33]
	v_or_b32_e32 v16, v16, v18
	v_lshl_add_u64 v[34:35], s[0:1], 0, v[16:17]
	global_load_dwordx4 v[28:31], v[34:35], off offset:-3072
	global_load_dwordx4 v[24:27], v[34:35], off offset:-2048
	global_load_dwordx4 v[20:23], v[34:35], off offset:-1024
	global_load_dwordx4 v[16:19], v[34:35], off
	s_branch .Lrn_A
